# loop-edge edit: GEMM K-loop scalar updates and exit compare moved in front of the loop-back barrier
# speedup vs baseline: 1.0003x; 1.0003x over previous
.LBB0_103:
	s_add_u32 s28, s24, 0xfffc0080
	s_addc_u32 s29, s25, -1
	s_add_i32 s68, 0, 0x10000
	s_cmp_eq_u32 s67, 12
	s_cselect_b32 s37, s0, s29
	s_cselect_b32 s36, s19, s28
	v_add_u32_e32 v0, s68, v147
	s_cselect_b32 s29, s17, s49
	s_cselect_b32 s28, s35, s48
	s_add_i32 s70, 0, 0x14000
	ds_read_b128 v[150:153], v0
	ds_read_b128 v[154:157], v0 offset:1024
	ds_read_b128 v[158:161], v0 offset:2048
	ds_read_b128 v[166:169], v0 offset:3072
	v_add_u32_e32 v0, s70, v147
	ds_read_b128 v[170:173], v0
	ds_read_b128 v[174:177], v0 offset:1024
	ds_read_b128 v[178:181], v0 offset:2048
	ds_read_b128 v[182:185], v0 offset:3072
	v_lshl_add_u64 v[202:203], s[24:25], 0, v[140:141]
	s_add_i32 m0, s15, 0xc000
	ds_read_b128 v[186:189], v148
	ds_read_b128 v[190:193], v148 offset:1024
	ds_read_b128 v[194:197], v148 offset:2048
	ds_read_b128 v[198:201], v148 offset:3072
	ds_read_b128 v[210:213], v148 offset:4096
	ds_read_b128 v[214:217], v148 offset:5120
	ds_read_b128 v[218:221], v148 offset:6144
	ds_read_b128 v[222:225], v148 offset:7168
	global_load_lds_dwordx4 v[202:203], off
	v_lshl_add_u64 v[202:203], s[24:25], 0, v[142:143]
	s_add_i32 m0, s15, 0xe000
	s_nop 0
	global_load_lds_dwordx4 v[202:203], off
	s_waitcnt vmcnt(8)
	s_waitcnt lgkmcnt(0)
	s_barrier
	s_setprio 1
	s_waitcnt lgkmcnt(0)
	v_mfma_f32_16x16x32_bf16 v[126:129], v[150:153], v[186:189], v[126:129]
	v_mfma_f32_16x16x32_bf16 v[122:125], v[158:161], v[186:189], v[122:125]
	v_mfma_f32_16x16x32_bf16 v[114:117], v[150:153], v[194:197], v[114:117]
	v_mfma_f32_16x16x32_bf16 v[106:109], v[158:161], v[194:197], v[106:109]
	v_mfma_f32_16x16x32_bf16 v[102:105], v[150:153], v[210:213], v[102:105]
	v_mfma_f32_16x16x32_bf16 v[94:97], v[158:161], v[210:213], v[94:97]
	v_mfma_f32_16x16x32_bf16 v[86:89], v[150:153], v[218:221], v[86:89]
	v_mfma_f32_16x16x32_bf16 v[78:81], v[158:161], v[218:221], v[78:81]
	v_mfma_f32_16x16x32_bf16 v[126:129], v[154:157], v[190:193], v[126:129]
	v_mfma_f32_16x16x32_bf16 v[122:125], v[166:169], v[190:193], v[122:125]
	v_mfma_f32_16x16x32_bf16 v[114:117], v[154:157], v[198:201], v[114:117]
	v_mfma_f32_16x16x32_bf16 v[106:109], v[166:169], v[198:201], v[106:109]
	v_mfma_f32_16x16x32_bf16 v[102:105], v[154:157], v[214:217], v[102:105]
	v_mfma_f32_16x16x32_bf16 v[94:97], v[166:169], v[214:217], v[94:97]
	v_mfma_f32_16x16x32_bf16 v[86:89], v[154:157], v[222:225], v[86:89]
	v_mfma_f32_16x16x32_bf16 v[78:81], v[166:169], v[222:225], v[78:81]
	s_setprio 0
	s_setprio 1
	v_mfma_f32_16x16x32_bf16 v[118:121], v[170:173], v[186:189], v[118:121]
	v_mfma_f32_16x16x32_bf16 v[110:113], v[178:181], v[186:189], v[110:113]
	v_mfma_f32_16x16x32_bf16 v[98:101], v[170:173], v[194:197], v[98:101]
	v_mfma_f32_16x16x32_bf16 v[90:93], v[178:181], v[194:197], v[90:93]
	v_mfma_f32_16x16x32_bf16 v[82:85], v[170:173], v[210:213], v[82:85]
	v_mfma_f32_16x16x32_bf16 v[74:77], v[178:181], v[210:213], v[74:77]
	v_mfma_f32_16x16x32_bf16 v[70:73], v[170:173], v[218:221], v[70:73]
	v_mfma_f32_16x16x32_bf16 v[66:69], v[178:181], v[218:221], v[66:69]
	v_mfma_f32_16x16x32_bf16 v[118:121], v[174:177], v[190:193], v[118:121]
	v_mfma_f32_16x16x32_bf16 v[110:113], v[182:185], v[190:193], v[110:113]
	v_mfma_f32_16x16x32_bf16 v[98:101], v[174:177], v[198:201], v[98:101]
	v_mfma_f32_16x16x32_bf16 v[90:93], v[182:185], v[198:201], v[90:93]
	v_mfma_f32_16x16x32_bf16 v[82:85], v[174:177], v[214:217], v[82:85]
	v_mfma_f32_16x16x32_bf16 v[74:77], v[182:185], v[214:217], v[74:77]
	v_mfma_f32_16x16x32_bf16 v[70:73], v[174:177], v[222:225], v[70:73]
	v_mfma_f32_16x16x32_bf16 v[66:69], v[182:185], v[222:225], v[66:69]
	s_setprio 0
	s_barrier
	s_add_i32 s68, s68, s55
	v_lshl_add_u64 v[202:203], s[28:29], 0, v[134:135]
	s_mov_b32 m0, s68
	ds_read_b128 v[186:189], v148 offset:16384
	ds_read_b128 v[190:193], v148 offset:17408
	ds_read_b128 v[194:197], v148 offset:18432
	ds_read_b128 v[198:201], v148 offset:19456
	ds_read_b128 v[210:213], v148 offset:20480
	ds_read_b128 v[214:217], v148 offset:21504
	ds_read_b128 v[218:221], v148 offset:22528
	ds_read_b128 v[222:225], v148 offset:23552
	global_load_lds_dwordx4 v[202:203], off
	s_add_i32 m0, s68, 0x2000
	s_add_u32 s68, s28, 0x40000
	v_lshl_add_u64 v[206:207], s[28:29], 0, v[130:131]
	s_addc_u32 s69, s29, 0
	s_add_i32 s70, s70, s55
	global_load_lds_dwordx4 v[206:207], off
	v_lshl_add_u64 v[226:227], s[68:69], 0, v[134:135]
	s_mov_b32 m0, s70
	v_lshl_add_u64 v[228:229], s[36:37], 0, v[132:133]
	global_load_lds_dwordx4 v[226:227], off
	v_lshl_add_u64 v[226:227], s[68:69], 0, v[130:131]
	s_add_i32 m0, s70, 0x2000
	s_nop 0
	global_load_lds_dwordx4 v[226:227], off
	v_lshl_add_u64 v[226:227], s[36:37], 0, v[136:137]
	s_mov_b32 m0, s15
	s_nop 0
	global_load_lds_dwordx4 v[226:227], off
	s_mov_b32 m0, s59
	s_nop 0
	global_load_lds_dwordx4 v[228:229], off
	s_waitcnt vmcnt(8)
	s_waitcnt lgkmcnt(0)
	s_barrier
	s_setprio 1
	s_waitcnt lgkmcnt(0)
	v_mfma_f32_16x16x32_bf16 v[62:65], v[150:153], v[186:189], v[62:65]
	v_mfma_f32_16x16x32_bf16 v[58:61], v[158:161], v[186:189], v[58:61]
	v_mfma_f32_16x16x32_bf16 v[54:57], v[150:153], v[194:197], v[54:57]
	v_mfma_f32_16x16x32_bf16 v[46:49], v[158:161], v[194:197], v[46:49]
	v_mfma_f32_16x16x32_bf16 v[38:41], v[150:153], v[210:213], v[38:41]
	v_mfma_f32_16x16x32_bf16 v[30:33], v[158:161], v[210:213], v[30:33]
	v_mfma_f32_16x16x32_bf16 v[22:25], v[150:153], v[218:221], v[22:25]
	v_mfma_f32_16x16x32_bf16 v[14:17], v[158:161], v[218:221], v[14:17]
	v_mfma_f32_16x16x32_bf16 v[62:65], v[154:157], v[190:193], v[62:65]
	v_mfma_f32_16x16x32_bf16 v[58:61], v[166:169], v[190:193], v[58:61]
	v_mfma_f32_16x16x32_bf16 v[54:57], v[154:157], v[198:201], v[54:57]
	v_mfma_f32_16x16x32_bf16 v[46:49], v[166:169], v[198:201], v[46:49]
	v_mfma_f32_16x16x32_bf16 v[38:41], v[154:157], v[214:217], v[38:41]
	v_mfma_f32_16x16x32_bf16 v[30:33], v[166:169], v[214:217], v[30:33]
	v_mfma_f32_16x16x32_bf16 v[22:25], v[154:157], v[222:225], v[22:25]
	v_mfma_f32_16x16x32_bf16 v[14:17], v[166:169], v[222:225], v[14:17]
	s_setprio 0
	s_setprio 1
	v_mfma_f32_16x16x32_bf16 v[50:53], v[170:173], v[186:189], v[50:53]
	v_mfma_f32_16x16x32_bf16 v[42:45], v[178:181], v[186:189], v[42:45]
	v_mfma_f32_16x16x32_bf16 v[34:37], v[170:173], v[194:197], v[34:37]
	v_mfma_f32_16x16x32_bf16 v[26:29], v[178:181], v[194:197], v[26:29]
	v_mfma_f32_16x16x32_bf16 v[18:21], v[170:173], v[210:213], v[18:21]
	v_mfma_f32_16x16x32_bf16 v[10:13], v[178:181], v[210:213], v[10:13]
	v_mfma_f32_16x16x32_bf16 v[6:9], v[170:173], v[218:221], v[6:9]
	v_mfma_f32_16x16x32_bf16 v[2:5], v[178:181], v[218:221], v[2:5]
	v_mfma_f32_16x16x32_bf16 v[50:53], v[174:177], v[190:193], v[50:53]
	v_mfma_f32_16x16x32_bf16 v[42:45], v[182:185], v[190:193], v[42:45]
	v_mfma_f32_16x16x32_bf16 v[34:37], v[174:177], v[198:201], v[34:37]
	v_mfma_f32_16x16x32_bf16 v[26:29], v[182:185], v[198:201], v[26:29]
	v_mfma_f32_16x16x32_bf16 v[18:21], v[174:177], v[214:217], v[18:21]
	v_mfma_f32_16x16x32_bf16 v[10:13], v[182:185], v[214:217], v[10:13]
	v_mfma_f32_16x16x32_bf16 v[6:9], v[174:177], v[222:225], v[6:9]
	v_mfma_f32_16x16x32_bf16 v[2:5], v[182:185], v[222:225], v[2:5]
	s_setprio 0
	s_barrier
	s_add_i32 s68, 0, 0x18000
	v_add_u32_e32 v0, s68, v147
	s_add_i32 s69, 0, 0x1c000
	ds_read_b128 v[150:153], v0
	ds_read_b128 v[154:157], v0 offset:1024
	ds_read_b128 v[158:161], v0 offset:2048
	ds_read_b128 v[166:169], v0 offset:3072
	v_add_u32_e32 v0, s69, v147
	ds_read_b128 v[170:173], v0
	ds_read_b128 v[174:177], v0 offset:1024
	ds_read_b128 v[178:181], v0 offset:2048
	ds_read_b128 v[182:185], v0 offset:3072
	s_add_u32 s36, s36, 0x40000
	s_addc_u32 s37, s37, 0
	s_mov_b32 m0, s60
	v_lshl_add_u64 v[230:231], s[36:37], 0, v[136:137]
	ds_read_b128 v[186:189], v148 offset:32768
	ds_read_b128 v[190:193], v148 offset:33792
	ds_read_b128 v[194:197], v148 offset:34816
	ds_read_b128 v[198:201], v148 offset:35840
	ds_read_b128 v[210:213], v148 offset:36864
	ds_read_b128 v[214:217], v148 offset:37888
	ds_read_b128 v[218:221], v148 offset:38912
	ds_read_b128 v[222:225], v148 offset:39936
	global_load_lds_dwordx4 v[230:231], off
	v_lshl_add_u64 v[230:231], s[36:37], 0, v[132:133]
	s_mov_b32 m0, s61
	s_nop 0
	global_load_lds_dwordx4 v[230:231], off
	s_waitcnt vmcnt(8)
	s_waitcnt lgkmcnt(0)
	s_barrier
	s_setprio 1
	s_waitcnt lgkmcnt(0)
	v_mfma_f32_16x16x32_bf16 v[126:129], v[150:153], v[186:189], v[126:129]
	v_mfma_f32_16x16x32_bf16 v[122:125], v[158:161], v[186:189], v[122:125]
	v_mfma_f32_16x16x32_bf16 v[114:117], v[150:153], v[194:197], v[114:117]
	v_mfma_f32_16x16x32_bf16 v[106:109], v[158:161], v[194:197], v[106:109]
	v_mfma_f32_16x16x32_bf16 v[102:105], v[150:153], v[210:213], v[102:105]
	v_mfma_f32_16x16x32_bf16 v[94:97], v[158:161], v[210:213], v[94:97]
	v_mfma_f32_16x16x32_bf16 v[86:89], v[150:153], v[218:221], v[86:89]
	v_mfma_f32_16x16x32_bf16 v[78:81], v[158:161], v[218:221], v[78:81]
	v_mfma_f32_16x16x32_bf16 v[126:129], v[154:157], v[190:193], v[126:129]
	v_mfma_f32_16x16x32_bf16 v[122:125], v[166:169], v[190:193], v[122:125]
	v_mfma_f32_16x16x32_bf16 v[114:117], v[154:157], v[198:201], v[114:117]
	v_mfma_f32_16x16x32_bf16 v[106:109], v[166:169], v[198:201], v[106:109]
	v_mfma_f32_16x16x32_bf16 v[102:105], v[154:157], v[214:217], v[102:105]
	v_mfma_f32_16x16x32_bf16 v[94:97], v[166:169], v[214:217], v[94:97]
	v_mfma_f32_16x16x32_bf16 v[86:89], v[154:157], v[222:225], v[86:89]
	v_mfma_f32_16x16x32_bf16 v[78:81], v[166:169], v[222:225], v[78:81]
	s_setprio 0
	s_setprio 1
	v_mfma_f32_16x16x32_bf16 v[118:121], v[170:173], v[186:189], v[118:121]
	v_mfma_f32_16x16x32_bf16 v[110:113], v[178:181], v[186:189], v[110:113]
	v_mfma_f32_16x16x32_bf16 v[98:101], v[170:173], v[194:197], v[98:101]
	v_mfma_f32_16x16x32_bf16 v[90:93], v[178:181], v[194:197], v[90:93]
	v_mfma_f32_16x16x32_bf16 v[82:85], v[170:173], v[210:213], v[82:85]
	v_mfma_f32_16x16x32_bf16 v[74:77], v[178:181], v[210:213], v[74:77]
	v_mfma_f32_16x16x32_bf16 v[70:73], v[170:173], v[218:221], v[70:73]
	v_mfma_f32_16x16x32_bf16 v[66:69], v[178:181], v[218:221], v[66:69]
	v_mfma_f32_16x16x32_bf16 v[118:121], v[174:177], v[190:193], v[118:121]
	v_mfma_f32_16x16x32_bf16 v[110:113], v[182:185], v[190:193], v[110:113]
	v_mfma_f32_16x16x32_bf16 v[98:101], v[174:177], v[198:201], v[98:101]
	v_mfma_f32_16x16x32_bf16 v[90:93], v[182:185], v[198:201], v[90:93]
	v_mfma_f32_16x16x32_bf16 v[82:85], v[174:177], v[214:217], v[82:85]
	v_mfma_f32_16x16x32_bf16 v[74:77], v[182:185], v[214:217], v[74:77]
	v_mfma_f32_16x16x32_bf16 v[70:73], v[174:177], v[222:225], v[70:73]
	v_mfma_f32_16x16x32_bf16 v[66:69], v[182:185], v[222:225], v[66:69]
	s_setprio 0
	s_barrier
	s_add_i32 s36, s68, s55
	v_lshl_add_u64 v[202:203], v[202:203], 0, s[4:5]
	s_mov_b32 m0, s36
	ds_read_b128 v[186:189], v148 offset:49152
	ds_read_b128 v[190:193], v148 offset:50176
	ds_read_b128 v[194:197], v148 offset:51200
	ds_read_b128 v[198:201], v148 offset:52224
	ds_read_b128 v[210:213], v148 offset:53248
	ds_read_b128 v[214:217], v148 offset:54272
	ds_read_b128 v[218:221], v148 offset:55296
	ds_read_b128 v[222:225], v148 offset:56320
	global_load_lds_dwordx4 v[202:203], off
	s_add_i32 m0, s36, 0x2000
	s_add_u32 s28, s28, 0x40080
	v_lshl_add_u64 v[202:203], v[206:207], 0, s[4:5]
	s_addc_u32 s29, s29, 0
	s_add_i32 s36, s69, s55
	global_load_lds_dwordx4 v[202:203], off
	v_lshl_add_u64 v[202:203], s[28:29], 0, v[134:135]
	s_mov_b32 m0, s36
	s_nop 0
	global_load_lds_dwordx4 v[202:203], off
	v_lshl_add_u64 v[202:203], s[28:29], 0, v[130:131]
	s_add_i32 m0, s36, 0x2000
	s_nop 0
	global_load_lds_dwordx4 v[202:203], off
	v_lshl_add_u64 v[202:203], v[226:227], 0, s[4:5]
	s_mov_b32 m0, s65
	s_nop 0
	global_load_lds_dwordx4 v[202:203], off
	v_lshl_add_u64 v[202:203], v[228:229], 0, s[4:5]
	s_mov_b32 m0, s66
	s_nop 0
	global_load_lds_dwordx4 v[202:203], off
	s_waitcnt vmcnt(8)
	s_waitcnt lgkmcnt(0)
	s_barrier
	s_setprio 1
	s_waitcnt lgkmcnt(0)
	v_mfma_f32_16x16x32_bf16 v[62:65], v[150:153], v[186:189], v[62:65]
	v_mfma_f32_16x16x32_bf16 v[58:61], v[158:161], v[186:189], v[58:61]
	v_mfma_f32_16x16x32_bf16 v[54:57], v[150:153], v[194:197], v[54:57]
	v_mfma_f32_16x16x32_bf16 v[46:49], v[158:161], v[194:197], v[46:49]
	v_mfma_f32_16x16x32_bf16 v[38:41], v[150:153], v[210:213], v[38:41]
	v_mfma_f32_16x16x32_bf16 v[30:33], v[158:161], v[210:213], v[30:33]
	v_mfma_f32_16x16x32_bf16 v[22:25], v[150:153], v[218:221], v[22:25]
	v_mfma_f32_16x16x32_bf16 v[14:17], v[158:161], v[218:221], v[14:17]
	v_mfma_f32_16x16x32_bf16 v[62:65], v[154:157], v[190:193], v[62:65]
	v_mfma_f32_16x16x32_bf16 v[58:61], v[166:169], v[190:193], v[58:61]
	v_mfma_f32_16x16x32_bf16 v[54:57], v[154:157], v[198:201], v[54:57]
	v_mfma_f32_16x16x32_bf16 v[46:49], v[166:169], v[198:201], v[46:49]
	v_mfma_f32_16x16x32_bf16 v[38:41], v[154:157], v[214:217], v[38:41]
	v_mfma_f32_16x16x32_bf16 v[30:33], v[166:169], v[214:217], v[30:33]
	v_mfma_f32_16x16x32_bf16 v[22:25], v[154:157], v[222:225], v[22:25]
	v_mfma_f32_16x16x32_bf16 v[14:17], v[166:169], v[222:225], v[14:17]
	s_setprio 0
	s_setprio 1
	v_mfma_f32_16x16x32_bf16 v[50:53], v[170:173], v[186:189], v[50:53]
	v_mfma_f32_16x16x32_bf16 v[42:45], v[178:181], v[186:189], v[42:45]
	v_mfma_f32_16x16x32_bf16 v[34:37], v[170:173], v[194:197], v[34:37]
	v_mfma_f32_16x16x32_bf16 v[26:29], v[178:181], v[194:197], v[26:29]
	v_mfma_f32_16x16x32_bf16 v[18:21], v[170:173], v[210:213], v[18:21]
	v_mfma_f32_16x16x32_bf16 v[10:13], v[178:181], v[210:213], v[10:13]
	v_mfma_f32_16x16x32_bf16 v[6:9], v[170:173], v[218:221], v[6:9]
	v_mfma_f32_16x16x32_bf16 v[2:5], v[178:181], v[218:221], v[2:5]
	v_mfma_f32_16x16x32_bf16 v[50:53], v[174:177], v[190:193], v[50:53]
	v_mfma_f32_16x16x32_bf16 v[42:45], v[182:185], v[190:193], v[42:45]
	v_mfma_f32_16x16x32_bf16 v[34:37], v[174:177], v[198:201], v[34:37]
	v_mfma_f32_16x16x32_bf16 v[26:29], v[182:185], v[198:201], v[26:29]
	v_mfma_f32_16x16x32_bf16 v[18:21], v[174:177], v[214:217], v[18:21]
	v_mfma_f32_16x16x32_bf16 v[10:13], v[182:185], v[214:217], v[10:13]
	v_mfma_f32_16x16x32_bf16 v[6:9], v[174:177], v[222:225], v[6:9]
	v_mfma_f32_16x16x32_bf16 v[2:5], v[182:185], v[222:225], v[2:5]
	s_setprio 0
	s_add_i32 s67, s67, 2
	s_add_u32 s24, s24, 0x100
	s_addc_u32 s25, s25, 0
	s_add_u32 s48, s48, 0x100
	s_addc_u32 s49, s49, 0
	s_cmp_gt_u32 s67, 13
	s_barrier
	s_cbranch_scc0 .LBB0_103
	s_and_b64 vcc, exec, s[12:13]
	s_cbranch_vccz .LBB0_106
	s_barrier

.LBB0_249:
	s_add_u32 s28, s8, 0xfffc0080
	s_addc_u32 s29, s9, -1
	s_add_i32 s57, 0, 0x10000
	s_cmp_eq_u32 s56, 12
	s_cselect_b32 s37, s21, s29
	s_cselect_b32 s36, s47, s28
	v_add_u32_e32 v0, s57, v157
	s_cselect_b32 s29, s19, s55
	s_cselect_b32 s28, s48, s49
	s_add_i32 s60, 0, 0x14000
	ds_read_b128 v[130:133], v0
	ds_read_b128 v[134:137], v0 offset:1024
	ds_read_b128 v[150:153], v0 offset:2048
	ds_read_b128 v[166:169], v0 offset:3072
	v_add_u32_e32 v0, s60, v157
	ds_read_b128 v[170:173], v0
	ds_read_b128 v[174:177], v0 offset:1024
	ds_read_b128 v[178:181], v0 offset:2048
	ds_read_b128 v[182:185], v0 offset:3072
	v_lshl_add_u64 v[154:155], s[8:9], 0, v[146:147]
	s_add_i32 m0, s40, 0xc000
	ds_read_b128 v[186:189], v159
	ds_read_b128 v[190:193], v159 offset:1024
	ds_read_b128 v[194:197], v159 offset:2048
	ds_read_b128 v[198:201], v159 offset:3072
	ds_read_b128 v[210:213], v159 offset:4096
	ds_read_b128 v[214:217], v159 offset:5120
	ds_read_b128 v[218:221], v159 offset:6144
	ds_read_b128 v[222:225], v159 offset:7168
	global_load_lds_dwordx4 v[154:155], off
	v_lshl_add_u64 v[154:155], s[8:9], 0, v[148:149]
	s_add_i32 m0, s40, 0xe000
	s_nop 0
	global_load_lds_dwordx4 v[154:155], off
	s_waitcnt vmcnt(8)
	s_waitcnt lgkmcnt(0)
	s_barrier
	s_setprio 1
	s_waitcnt lgkmcnt(0)
	v_mfma_f32_16x16x32_bf16 v[126:129], v[130:133], v[186:189], v[126:129]
	v_mfma_f32_16x16x32_bf16 v[122:125], v[150:153], v[186:189], v[122:125]
	v_mfma_f32_16x16x32_bf16 v[118:121], v[130:133], v[194:197], v[118:121]
	v_mfma_f32_16x16x32_bf16 v[114:117], v[150:153], v[194:197], v[114:117]
	v_mfma_f32_16x16x32_bf16 v[110:113], v[130:133], v[210:213], v[110:113]
	v_mfma_f32_16x16x32_bf16 v[106:109], v[150:153], v[210:213], v[106:109]
	v_mfma_f32_16x16x32_bf16 v[102:105], v[130:133], v[218:221], v[102:105]
	v_mfma_f32_16x16x32_bf16 v[98:101], v[150:153], v[218:221], v[98:101]
	v_mfma_f32_16x16x32_bf16 v[126:129], v[134:137], v[190:193], v[126:129]
	v_mfma_f32_16x16x32_bf16 v[122:125], v[166:169], v[190:193], v[122:125]
	v_mfma_f32_16x16x32_bf16 v[118:121], v[134:137], v[198:201], v[118:121]
	v_mfma_f32_16x16x32_bf16 v[114:117], v[166:169], v[198:201], v[114:117]
	v_mfma_f32_16x16x32_bf16 v[110:113], v[134:137], v[214:217], v[110:113]
	v_mfma_f32_16x16x32_bf16 v[106:109], v[166:169], v[214:217], v[106:109]
	v_mfma_f32_16x16x32_bf16 v[102:105], v[134:137], v[222:225], v[102:105]
	v_mfma_f32_16x16x32_bf16 v[98:101], v[166:169], v[222:225], v[98:101]
	s_setprio 0
	s_setprio 1
	v_mfma_f32_16x16x32_bf16 v[62:65], v[170:173], v[186:189], v[62:65]
	v_mfma_f32_16x16x32_bf16 v[58:61], v[178:181], v[186:189], v[58:61]
	v_mfma_f32_16x16x32_bf16 v[54:57], v[170:173], v[194:197], v[54:57]
	v_mfma_f32_16x16x32_bf16 v[50:53], v[178:181], v[194:197], v[50:53]
	v_mfma_f32_16x16x32_bf16 v[46:49], v[170:173], v[210:213], v[46:49]
	v_mfma_f32_16x16x32_bf16 v[42:45], v[178:181], v[210:213], v[42:45]
	v_mfma_f32_16x16x32_bf16 v[38:41], v[170:173], v[218:221], v[38:41]
	v_mfma_f32_16x16x32_bf16 v[34:37], v[178:181], v[218:221], v[34:37]
	v_mfma_f32_16x16x32_bf16 v[62:65], v[174:177], v[190:193], v[62:65]
	v_mfma_f32_16x16x32_bf16 v[58:61], v[182:185], v[190:193], v[58:61]
	v_mfma_f32_16x16x32_bf16 v[54:57], v[174:177], v[198:201], v[54:57]
	v_mfma_f32_16x16x32_bf16 v[50:53], v[182:185], v[198:201], v[50:53]
	v_mfma_f32_16x16x32_bf16 v[46:49], v[174:177], v[214:217], v[46:49]
	v_mfma_f32_16x16x32_bf16 v[42:45], v[182:185], v[214:217], v[42:45]
	v_mfma_f32_16x16x32_bf16 v[38:41], v[174:177], v[222:225], v[38:41]
	v_mfma_f32_16x16x32_bf16 v[34:37], v[182:185], v[222:225], v[34:37]
	s_setprio 0
	s_barrier
	s_add_i32 s57, s57, s39
	v_lshl_add_u64 v[154:155], s[28:29], 0, v[142:143]
	s_mov_b32 m0, s57
	ds_read_b128 v[186:189], v159 offset:16384
	ds_read_b128 v[190:193], v159 offset:17408
	ds_read_b128 v[194:197], v159 offset:18432
	ds_read_b128 v[198:201], v159 offset:19456
	ds_read_b128 v[210:213], v159 offset:20480
	ds_read_b128 v[214:217], v159 offset:21504
	ds_read_b128 v[218:221], v159 offset:22528
	ds_read_b128 v[222:225], v159 offset:23552
	global_load_lds_dwordx4 v[154:155], off
	s_add_i32 m0, s57, 0x2000
	s_add_u32 s58, s28, 0x40000
	v_lshl_add_u64 v[160:161], s[28:29], 0, v[138:139]
	s_addc_u32 s59, s29, 0
	s_add_i32 s57, s60, s39
	global_load_lds_dwordx4 v[160:161], off
	v_lshl_add_u64 v[202:203], s[58:59], 0, v[142:143]
	s_mov_b32 m0, s57
	v_lshl_add_u64 v[206:207], s[36:37], 0, v[140:141]
	global_load_lds_dwordx4 v[202:203], off
	v_lshl_add_u64 v[202:203], s[58:59], 0, v[138:139]
	s_add_i32 m0, s57, 0x2000
	s_nop 0
	global_load_lds_dwordx4 v[202:203], off
	v_lshl_add_u64 v[202:203], s[36:37], 0, v[144:145]
	s_mov_b32 m0, s40
	s_nop 0
	global_load_lds_dwordx4 v[202:203], off
	s_mov_b32 m0, s41
	s_nop 0
	global_load_lds_dwordx4 v[206:207], off
	s_waitcnt vmcnt(8)
	s_waitcnt lgkmcnt(0)
	s_barrier
	s_setprio 1
	s_waitcnt lgkmcnt(0)
	v_mfma_f32_16x16x32_bf16 v[94:97], v[130:133], v[186:189], v[94:97]
	v_mfma_f32_16x16x32_bf16 v[90:93], v[150:153], v[186:189], v[90:93]
	v_mfma_f32_16x16x32_bf16 v[86:89], v[130:133], v[194:197], v[86:89]
	v_mfma_f32_16x16x32_bf16 v[82:85], v[150:153], v[194:197], v[82:85]
	v_mfma_f32_16x16x32_bf16 v[78:81], v[130:133], v[210:213], v[78:81]
	v_mfma_f32_16x16x32_bf16 v[74:77], v[150:153], v[210:213], v[74:77]
	v_mfma_f32_16x16x32_bf16 v[70:73], v[130:133], v[218:221], v[70:73]
	v_mfma_f32_16x16x32_bf16 v[66:69], v[150:153], v[218:221], v[66:69]
	v_mfma_f32_16x16x32_bf16 v[94:97], v[134:137], v[190:193], v[94:97]
	v_mfma_f32_16x16x32_bf16 v[90:93], v[166:169], v[190:193], v[90:93]
	v_mfma_f32_16x16x32_bf16 v[86:89], v[134:137], v[198:201], v[86:89]
	v_mfma_f32_16x16x32_bf16 v[82:85], v[166:169], v[198:201], v[82:85]
	v_mfma_f32_16x16x32_bf16 v[78:81], v[134:137], v[214:217], v[78:81]
	v_mfma_f32_16x16x32_bf16 v[74:77], v[166:169], v[214:217], v[74:77]
	v_mfma_f32_16x16x32_bf16 v[70:73], v[134:137], v[222:225], v[70:73]
	v_mfma_f32_16x16x32_bf16 v[66:69], v[166:169], v[222:225], v[66:69]
	s_setprio 0
	s_setprio 1
	v_mfma_f32_16x16x32_bf16 v[30:33], v[170:173], v[186:189], v[30:33]
	v_mfma_f32_16x16x32_bf16 v[26:29], v[178:181], v[186:189], v[26:29]
	v_mfma_f32_16x16x32_bf16 v[22:25], v[170:173], v[194:197], v[22:25]
	v_mfma_f32_16x16x32_bf16 v[18:21], v[178:181], v[194:197], v[18:21]
	v_mfma_f32_16x16x32_bf16 v[14:17], v[170:173], v[210:213], v[14:17]
	v_mfma_f32_16x16x32_bf16 v[10:13], v[178:181], v[210:213], v[10:13]
	v_mfma_f32_16x16x32_bf16 v[6:9], v[170:173], v[218:221], v[6:9]
	v_mfma_f32_16x16x32_bf16 v[2:5], v[178:181], v[218:221], v[2:5]
	v_mfma_f32_16x16x32_bf16 v[30:33], v[174:177], v[190:193], v[30:33]
	v_mfma_f32_16x16x32_bf16 v[26:29], v[182:185], v[190:193], v[26:29]
	v_mfma_f32_16x16x32_bf16 v[22:25], v[174:177], v[198:201], v[22:25]
	v_mfma_f32_16x16x32_bf16 v[18:21], v[182:185], v[198:201], v[18:21]
	v_mfma_f32_16x16x32_bf16 v[14:17], v[174:177], v[214:217], v[14:17]
	v_mfma_f32_16x16x32_bf16 v[10:13], v[182:185], v[214:217], v[10:13]
	v_mfma_f32_16x16x32_bf16 v[6:9], v[174:177], v[222:225], v[6:9]
	v_mfma_f32_16x16x32_bf16 v[2:5], v[182:185], v[222:225], v[2:5]
	s_setprio 0
	s_barrier
	s_add_i32 s57, 0, 0x18000
	v_add_u32_e32 v0, s57, v157
	s_add_i32 s58, 0, 0x1c000
	ds_read_b128 v[130:133], v0
	ds_read_b128 v[134:137], v0 offset:1024
	ds_read_b128 v[150:153], v0 offset:2048
	ds_read_b128 v[166:169], v0 offset:3072
	v_add_u32_e32 v0, s58, v157
	ds_read_b128 v[170:173], v0
	ds_read_b128 v[174:177], v0 offset:1024
	ds_read_b128 v[178:181], v0 offset:2048
	ds_read_b128 v[182:185], v0 offset:3072
	s_add_u32 s36, s36, 0x40000
	s_addc_u32 s37, s37, 0
	s_mov_b32 m0, s42
	v_lshl_add_u64 v[226:227], s[36:37], 0, v[144:145]
	ds_read_b128 v[186:189], v159 offset:32768
	ds_read_b128 v[190:193], v159 offset:33792
	ds_read_b128 v[194:197], v159 offset:34816
	ds_read_b128 v[198:201], v159 offset:35840
	ds_read_b128 v[210:213], v159 offset:36864
	ds_read_b128 v[214:217], v159 offset:37888
	ds_read_b128 v[218:221], v159 offset:38912
	ds_read_b128 v[222:225], v159 offset:39936
	global_load_lds_dwordx4 v[226:227], off
	v_lshl_add_u64 v[226:227], s[36:37], 0, v[140:141]
	s_mov_b32 m0, s43
	s_nop 0
	global_load_lds_dwordx4 v[226:227], off
	s_waitcnt vmcnt(8)
	s_waitcnt lgkmcnt(0)
	s_barrier
	s_setprio 1
	s_waitcnt lgkmcnt(0)
	v_mfma_f32_16x16x32_bf16 v[126:129], v[130:133], v[186:189], v[126:129]
	v_mfma_f32_16x16x32_bf16 v[122:125], v[150:153], v[186:189], v[122:125]
	v_mfma_f32_16x16x32_bf16 v[118:121], v[130:133], v[194:197], v[118:121]
	v_mfma_f32_16x16x32_bf16 v[114:117], v[150:153], v[194:197], v[114:117]
	v_mfma_f32_16x16x32_bf16 v[110:113], v[130:133], v[210:213], v[110:113]
	v_mfma_f32_16x16x32_bf16 v[106:109], v[150:153], v[210:213], v[106:109]
	v_mfma_f32_16x16x32_bf16 v[102:105], v[130:133], v[218:221], v[102:105]
	v_mfma_f32_16x16x32_bf16 v[98:101], v[150:153], v[218:221], v[98:101]
	v_mfma_f32_16x16x32_bf16 v[126:129], v[134:137], v[190:193], v[126:129]
	v_mfma_f32_16x16x32_bf16 v[122:125], v[166:169], v[190:193], v[122:125]
	v_mfma_f32_16x16x32_bf16 v[118:121], v[134:137], v[198:201], v[118:121]
	v_mfma_f32_16x16x32_bf16 v[114:117], v[166:169], v[198:201], v[114:117]
	v_mfma_f32_16x16x32_bf16 v[110:113], v[134:137], v[214:217], v[110:113]
	v_mfma_f32_16x16x32_bf16 v[106:109], v[166:169], v[214:217], v[106:109]
	v_mfma_f32_16x16x32_bf16 v[102:105], v[134:137], v[222:225], v[102:105]
	v_mfma_f32_16x16x32_bf16 v[98:101], v[166:169], v[222:225], v[98:101]
	s_setprio 0
	s_setprio 1
	v_mfma_f32_16x16x32_bf16 v[62:65], v[170:173], v[186:189], v[62:65]
	v_mfma_f32_16x16x32_bf16 v[58:61], v[178:181], v[186:189], v[58:61]
	v_mfma_f32_16x16x32_bf16 v[54:57], v[170:173], v[194:197], v[54:57]
	v_mfma_f32_16x16x32_bf16 v[50:53], v[178:181], v[194:197], v[50:53]
	v_mfma_f32_16x16x32_bf16 v[46:49], v[170:173], v[210:213], v[46:49]
	v_mfma_f32_16x16x32_bf16 v[42:45], v[178:181], v[210:213], v[42:45]
	v_mfma_f32_16x16x32_bf16 v[38:41], v[170:173], v[218:221], v[38:41]
	v_mfma_f32_16x16x32_bf16 v[34:37], v[178:181], v[218:221], v[34:37]
	v_mfma_f32_16x16x32_bf16 v[62:65], v[174:177], v[190:193], v[62:65]
	v_mfma_f32_16x16x32_bf16 v[58:61], v[182:185], v[190:193], v[58:61]
	v_mfma_f32_16x16x32_bf16 v[54:57], v[174:177], v[198:201], v[54:57]
	v_mfma_f32_16x16x32_bf16 v[50:53], v[182:185], v[198:201], v[50:53]
	v_mfma_f32_16x16x32_bf16 v[46:49], v[174:177], v[214:217], v[46:49]
	v_mfma_f32_16x16x32_bf16 v[42:45], v[182:185], v[214:217], v[42:45]
	v_mfma_f32_16x16x32_bf16 v[38:41], v[174:177], v[222:225], v[38:41]
	v_mfma_f32_16x16x32_bf16 v[34:37], v[182:185], v[222:225], v[34:37]
	s_setprio 0
	s_barrier
	s_add_i32 s36, s57, s39
	v_lshl_add_u64 v[154:155], v[154:155], 0, s[4:5]
	s_mov_b32 m0, s36
	ds_read_b128 v[186:189], v159 offset:49152
	ds_read_b128 v[190:193], v159 offset:50176
	ds_read_b128 v[194:197], v159 offset:51200
	ds_read_b128 v[198:201], v159 offset:52224
	ds_read_b128 v[210:213], v159 offset:53248
	ds_read_b128 v[214:217], v159 offset:54272
	ds_read_b128 v[218:221], v159 offset:55296
	ds_read_b128 v[222:225], v159 offset:56320
	global_load_lds_dwordx4 v[154:155], off
	s_add_i32 m0, s36, 0x2000
	s_add_u32 s28, s28, 0x40080
	v_lshl_add_u64 v[154:155], v[160:161], 0, s[4:5]
	s_addc_u32 s29, s29, 0
	s_add_i32 s36, s58, s39
	global_load_lds_dwordx4 v[154:155], off
	v_lshl_add_u64 v[154:155], s[28:29], 0, v[142:143]
	s_mov_b32 m0, s36
	s_nop 0
	global_load_lds_dwordx4 v[154:155], off
	v_lshl_add_u64 v[154:155], s[28:29], 0, v[138:139]
	s_add_i32 m0, s36, 0x2000
	s_nop 0
	global_load_lds_dwordx4 v[154:155], off
	v_lshl_add_u64 v[154:155], v[202:203], 0, s[4:5]
	s_mov_b32 m0, s52
	s_nop 0
	global_load_lds_dwordx4 v[154:155], off
	v_lshl_add_u64 v[154:155], v[206:207], 0, s[4:5]
	s_mov_b32 m0, s53
	s_nop 0
	global_load_lds_dwordx4 v[154:155], off
	s_waitcnt vmcnt(8)
	s_waitcnt lgkmcnt(0)
	s_barrier
	s_setprio 1
	s_waitcnt lgkmcnt(0)
	v_mfma_f32_16x16x32_bf16 v[94:97], v[130:133], v[186:189], v[94:97]
	v_mfma_f32_16x16x32_bf16 v[90:93], v[150:153], v[186:189], v[90:93]
	v_mfma_f32_16x16x32_bf16 v[86:89], v[130:133], v[194:197], v[86:89]
	v_mfma_f32_16x16x32_bf16 v[82:85], v[150:153], v[194:197], v[82:85]
	v_mfma_f32_16x16x32_bf16 v[78:81], v[130:133], v[210:213], v[78:81]
	v_mfma_f32_16x16x32_bf16 v[74:77], v[150:153], v[210:213], v[74:77]
	v_mfma_f32_16x16x32_bf16 v[70:73], v[130:133], v[218:221], v[70:73]
	v_mfma_f32_16x16x32_bf16 v[66:69], v[150:153], v[218:221], v[66:69]
	v_mfma_f32_16x16x32_bf16 v[94:97], v[134:137], v[190:193], v[94:97]
	v_mfma_f32_16x16x32_bf16 v[90:93], v[166:169], v[190:193], v[90:93]
	v_mfma_f32_16x16x32_bf16 v[86:89], v[134:137], v[198:201], v[86:89]
	v_mfma_f32_16x16x32_bf16 v[82:85], v[166:169], v[198:201], v[82:85]
	v_mfma_f32_16x16x32_bf16 v[78:81], v[134:137], v[214:217], v[78:81]
	v_mfma_f32_16x16x32_bf16 v[74:77], v[166:169], v[214:217], v[74:77]
	v_mfma_f32_16x16x32_bf16 v[70:73], v[134:137], v[222:225], v[70:73]
	v_mfma_f32_16x16x32_bf16 v[66:69], v[166:169], v[222:225], v[66:69]
	s_setprio 0
	s_setprio 1
	v_mfma_f32_16x16x32_bf16 v[30:33], v[170:173], v[186:189], v[30:33]
	v_mfma_f32_16x16x32_bf16 v[26:29], v[178:181], v[186:189], v[26:29]
	v_mfma_f32_16x16x32_bf16 v[22:25], v[170:173], v[194:197], v[22:25]
	v_mfma_f32_16x16x32_bf16 v[18:21], v[178:181], v[194:197], v[18:21]
	v_mfma_f32_16x16x32_bf16 v[14:17], v[170:173], v[210:213], v[14:17]
	v_mfma_f32_16x16x32_bf16 v[10:13], v[178:181], v[210:213], v[10:13]
	v_mfma_f32_16x16x32_bf16 v[6:9], v[170:173], v[218:221], v[6:9]
	v_mfma_f32_16x16x32_bf16 v[2:5], v[178:181], v[218:221], v[2:5]
	v_mfma_f32_16x16x32_bf16 v[30:33], v[174:177], v[190:193], v[30:33]
	v_mfma_f32_16x16x32_bf16 v[26:29], v[182:185], v[190:193], v[26:29]
	v_mfma_f32_16x16x32_bf16 v[22:25], v[174:177], v[198:201], v[22:25]
	v_mfma_f32_16x16x32_bf16 v[18:21], v[182:185], v[198:201], v[18:21]
	v_mfma_f32_16x16x32_bf16 v[14:17], v[174:177], v[214:217], v[14:17]
	v_mfma_f32_16x16x32_bf16 v[10:13], v[182:185], v[214:217], v[10:13]
	v_mfma_f32_16x16x32_bf16 v[6:9], v[174:177], v[222:225], v[6:9]
	v_mfma_f32_16x16x32_bf16 v[2:5], v[182:185], v[222:225], v[2:5]
	s_setprio 0
	s_add_i32 s56, s56, 2
	s_add_u32 s8, s8, 0x100
	s_addc_u32 s9, s9, 0
	s_add_u32 s49, s49, 0x100
	s_addc_u32 s55, s55, 0
	s_cmp_gt_u32 s56, 13
	s_barrier
	s_cbranch_scc0 .LBB0_249
	s_and_b64 vcc, exec, s[12:13]
	s_cbranch_vccz .LBB0_252
	s_barrier

.LBB0_527:
	s_add_i32 s99, s96, 2
	s_add_u32 vcc_lo, s88, s94
	s_addc_u32 s97, s89, s95
	s_add_u32 s20, s90, s94
	s_addc_u32 vcc_hi, s91, s95
	s_add_i32 s78, 0, 0x10000
	s_cmp_eq_u32 s21, s96
	s_cselect_b32 s97, s11, s97
	s_cselect_b32 s96, s10, vcc_lo
	v_add_u32_e32 v160, s78, v146
	s_cselect_b32 vcc_hi, s93, vcc_hi
	s_cselect_b32 vcc_lo, s92, s20
	s_add_i32 s20, 0, 0x14000
	ds_read_b128 v[148:151], v160
	ds_read_b128 v[152:155], v160 offset:1024
	ds_read_b128 v[156:159], v160 offset:2048
	ds_read_b128 v[166:169], v160 offset:3072
	v_add_u32_e32 v160, s20, v146
	ds_read_b128 v[170:173], v160
	ds_read_b128 v[174:177], v160 offset:1024
	ds_read_b128 v[178:181], v160 offset:2048
	ds_read_b128 v[182:185], v160 offset:3072
	v_lshl_add_u64 v[160:161], s[88:89], 0, v[142:143]
	s_add_i32 m0, s14, 0xc000
	ds_read_b128 v[186:189], v147
	ds_read_b128 v[190:193], v147 offset:1024
	ds_read_b128 v[194:197], v147 offset:2048
	ds_read_b128 v[198:201], v147 offset:3072
	ds_read_b128 v[210:213], v147 offset:4096
	ds_read_b128 v[214:217], v147 offset:5120
	ds_read_b128 v[218:221], v147 offset:6144
	ds_read_b128 v[222:225], v147 offset:7168
	global_load_lds_dwordx4 v[160:161], off
	v_lshl_add_u64 v[160:161], s[88:89], 0, v[140:141]
	s_add_i32 m0, s14, 0xe000
	s_nop 0
	global_load_lds_dwordx4 v[160:161], off
	s_waitcnt vmcnt(8)
	s_waitcnt lgkmcnt(0)
	s_barrier
	s_setprio 1
	s_waitcnt lgkmcnt(0)
	v_mfma_f32_16x16x32_bf16 v[126:129], v[148:151], v[186:189], v[126:129]
	v_mfma_f32_16x16x32_bf16 v[122:125], v[156:159], v[186:189], v[122:125]
	v_mfma_f32_16x16x32_bf16 v[110:113], v[148:151], v[194:197], v[110:113]
	v_mfma_f32_16x16x32_bf16 v[106:109], v[156:159], v[194:197], v[106:109]
	v_mfma_f32_16x16x32_bf16 v[86:89], v[148:151], v[210:213], v[86:89]
	v_mfma_f32_16x16x32_bf16 v[82:85], v[156:159], v[210:213], v[82:85]
	v_mfma_f32_16x16x32_bf16 v[70:73], v[148:151], v[218:221], v[70:73]
	v_mfma_f32_16x16x32_bf16 v[66:69], v[156:159], v[218:221], v[66:69]
	v_mfma_f32_16x16x32_bf16 v[126:129], v[152:155], v[190:193], v[126:129]
	v_mfma_f32_16x16x32_bf16 v[122:125], v[166:169], v[190:193], v[122:125]
	v_mfma_f32_16x16x32_bf16 v[110:113], v[152:155], v[198:201], v[110:113]
	v_mfma_f32_16x16x32_bf16 v[106:109], v[166:169], v[198:201], v[106:109]
	v_mfma_f32_16x16x32_bf16 v[86:89], v[152:155], v[214:217], v[86:89]
	v_mfma_f32_16x16x32_bf16 v[82:85], v[166:169], v[214:217], v[82:85]
	v_mfma_f32_16x16x32_bf16 v[70:73], v[152:155], v[222:225], v[70:73]
	v_mfma_f32_16x16x32_bf16 v[66:69], v[166:169], v[222:225], v[66:69]
	s_setprio 0
	s_setprio 1
	v_mfma_f32_16x16x32_bf16 v[118:121], v[170:173], v[186:189], v[118:121]
	v_mfma_f32_16x16x32_bf16 v[114:117], v[178:181], v[186:189], v[114:117]
	v_mfma_f32_16x16x32_bf16 v[102:105], v[170:173], v[194:197], v[102:105]
	v_mfma_f32_16x16x32_bf16 v[98:101], v[178:181], v[194:197], v[98:101]
	v_mfma_f32_16x16x32_bf16 v[90:93], v[170:173], v[210:213], v[90:93]
	v_mfma_f32_16x16x32_bf16 v[94:97], v[178:181], v[210:213], v[94:97]
	v_mfma_f32_16x16x32_bf16 v[74:77], v[170:173], v[218:221], v[74:77]
	v_mfma_f32_16x16x32_bf16 v[78:81], v[178:181], v[218:221], v[78:81]
	v_mfma_f32_16x16x32_bf16 v[118:121], v[174:177], v[190:193], v[118:121]
	v_mfma_f32_16x16x32_bf16 v[114:117], v[182:185], v[190:193], v[114:117]
	v_mfma_f32_16x16x32_bf16 v[102:105], v[174:177], v[198:201], v[102:105]
	v_mfma_f32_16x16x32_bf16 v[98:101], v[182:185], v[198:201], v[98:101]
	v_mfma_f32_16x16x32_bf16 v[90:93], v[174:177], v[214:217], v[90:93]
	v_mfma_f32_16x16x32_bf16 v[94:97], v[182:185], v[214:217], v[94:97]
	v_mfma_f32_16x16x32_bf16 v[74:77], v[174:177], v[222:225], v[74:77]
	v_mfma_f32_16x16x32_bf16 v[78:81], v[182:185], v[222:225], v[78:81]
	s_setprio 0
	s_barrier
	s_add_i32 s78, s78, s83
	v_lshl_add_u64 v[160:161], vcc, 0, v[0:1]
	s_mov_b32 m0, s78
	ds_read_b128 v[186:189], v147 offset:16384
	ds_read_b128 v[190:193], v147 offset:17408
	ds_read_b128 v[194:197], v147 offset:18432
	ds_read_b128 v[198:201], v147 offset:19456
	ds_read_b128 v[210:213], v147 offset:20480
	ds_read_b128 v[214:217], v147 offset:21504
	ds_read_b128 v[218:221], v147 offset:22528
	ds_read_b128 v[222:225], v147 offset:23552
	global_load_lds_dwordx4 v[160:161], off
	s_add_i32 m0, s78, 0x2000
	v_lshl_add_u64 v[202:203], vcc, 0, v[130:131]
	s_add_u32 vcc_lo, vcc_lo, s76
	s_addc_u32 vcc_hi, vcc_hi, 0
	s_add_i32 s20, s20, s83
	global_load_lds_dwordx4 v[202:203], off
	v_lshl_add_u64 v[206:207], vcc, 0, v[0:1]
	s_mov_b32 m0, s20
	v_lshl_add_u64 v[226:227], vcc, 0, v[130:131]
	global_load_lds_dwordx4 v[206:207], off
	s_add_i32 m0, s20, 0x2000
	v_lshl_add_u64 v[228:229], s[96:97], 0, v[134:135]
	global_load_lds_dwordx4 v[226:227], off
	s_mov_b32 m0, s14
	v_lshl_add_u64 v[230:231], s[96:97], 0, v[132:133]
	global_load_lds_dwordx4 v[228:229], off
	s_mov_b32 m0, s15
	s_nop 0
	global_load_lds_dwordx4 v[230:231], off
	s_waitcnt vmcnt(8)
	s_waitcnt lgkmcnt(0)
	s_barrier
	s_setprio 1
	s_waitcnt lgkmcnt(0)
	v_mfma_f32_16x16x32_bf16 v[54:57], v[148:151], v[186:189], v[54:57]
	v_mfma_f32_16x16x32_bf16 v[50:53], v[156:159], v[186:189], v[50:53]
	v_mfma_f32_16x16x32_bf16 v[38:41], v[148:151], v[194:197], v[38:41]
	v_mfma_f32_16x16x32_bf16 v[34:37], v[156:159], v[194:197], v[34:37]
	v_mfma_f32_16x16x32_bf16 v[22:25], v[148:151], v[210:213], v[22:25]
	v_mfma_f32_16x16x32_bf16 v[18:21], v[156:159], v[210:213], v[18:21]
	v_mfma_f32_16x16x32_bf16 v[6:9], v[148:151], v[218:221], v[6:9]
	v_mfma_f32_16x16x32_bf16 v[2:5], v[156:159], v[218:221], v[2:5]
	v_mfma_f32_16x16x32_bf16 v[54:57], v[152:155], v[190:193], v[54:57]
	v_mfma_f32_16x16x32_bf16 v[50:53], v[166:169], v[190:193], v[50:53]
	v_mfma_f32_16x16x32_bf16 v[38:41], v[152:155], v[198:201], v[38:41]
	v_mfma_f32_16x16x32_bf16 v[34:37], v[166:169], v[198:201], v[34:37]
	v_mfma_f32_16x16x32_bf16 v[22:25], v[152:155], v[214:217], v[22:25]
	v_mfma_f32_16x16x32_bf16 v[18:21], v[166:169], v[214:217], v[18:21]
	v_mfma_f32_16x16x32_bf16 v[6:9], v[152:155], v[222:225], v[6:9]
	v_mfma_f32_16x16x32_bf16 v[2:5], v[166:169], v[222:225], v[2:5]
	s_setprio 0
	s_setprio 1
	v_mfma_f32_16x16x32_bf16 v[58:61], v[170:173], v[186:189], v[58:61]
	v_mfma_f32_16x16x32_bf16 v[62:65], v[178:181], v[186:189], v[62:65]
	v_mfma_f32_16x16x32_bf16 v[42:45], v[170:173], v[194:197], v[42:45]
	v_mfma_f32_16x16x32_bf16 v[46:49], v[178:181], v[194:197], v[46:49]
	v_mfma_f32_16x16x32_bf16 v[26:29], v[170:173], v[210:213], v[26:29]
	v_mfma_f32_16x16x32_bf16 v[30:33], v[178:181], v[210:213], v[30:33]
	v_mfma_f32_16x16x32_bf16 v[10:13], v[170:173], v[218:221], v[10:13]
	v_mfma_f32_16x16x32_bf16 v[14:17], v[178:181], v[218:221], v[14:17]
	v_mfma_f32_16x16x32_bf16 v[58:61], v[174:177], v[190:193], v[58:61]
	v_mfma_f32_16x16x32_bf16 v[62:65], v[182:185], v[190:193], v[62:65]
	v_mfma_f32_16x16x32_bf16 v[42:45], v[174:177], v[198:201], v[42:45]
	v_mfma_f32_16x16x32_bf16 v[46:49], v[182:185], v[198:201], v[46:49]
	v_mfma_f32_16x16x32_bf16 v[26:29], v[174:177], v[214:217], v[26:29]
	v_mfma_f32_16x16x32_bf16 v[30:33], v[182:185], v[214:217], v[30:33]
	v_mfma_f32_16x16x32_bf16 v[10:13], v[174:177], v[222:225], v[10:13]
	v_mfma_f32_16x16x32_bf16 v[14:17], v[182:185], v[222:225], v[14:17]
	s_setprio 0
	s_barrier
	s_add_i32 s20, 0, 0x18000
	s_add_i32 s78, 0, 0x1c000
	v_add_u32_e32 v166, s20, v146
	v_add_u32_e32 v182, s78, v146
	ds_read_b128 v[148:151], v166
	ds_read_b128 v[152:155], v166 offset:1024
	ds_read_b128 v[156:159], v166 offset:2048
	ds_read_b128 v[166:169], v166 offset:3072
	ds_read_b128 v[170:173], v182
	ds_read_b128 v[174:177], v182 offset:1024
	ds_read_b128 v[178:181], v182 offset:2048
	ds_read_b128 v[182:185], v182 offset:3072
	s_add_u32 s96, s96, s76
	s_addc_u32 s97, s97, 0
	s_mov_b32 m0, s48
	v_lshl_add_u64 v[232:233], s[96:97], 0, v[134:135]
	ds_read_b128 v[186:189], v147 offset:32768
	ds_read_b128 v[190:193], v147 offset:33792
	ds_read_b128 v[194:197], v147 offset:34816
	ds_read_b128 v[198:201], v147 offset:35840
	ds_read_b128 v[210:213], v147 offset:36864
	ds_read_b128 v[214:217], v147 offset:37888
	ds_read_b128 v[218:221], v147 offset:38912
	ds_read_b128 v[222:225], v147 offset:39936
	global_load_lds_dwordx4 v[232:233], off
	v_lshl_add_u64 v[232:233], s[96:97], 0, v[132:133]
	s_mov_b32 m0, s49
	s_nop 0
	global_load_lds_dwordx4 v[232:233], off
	s_waitcnt vmcnt(8)
	s_waitcnt lgkmcnt(0)
	s_barrier
	s_setprio 1
	s_waitcnt lgkmcnt(0)
	v_mfma_f32_16x16x32_bf16 v[126:129], v[148:151], v[186:189], v[126:129]
	v_mfma_f32_16x16x32_bf16 v[122:125], v[156:159], v[186:189], v[122:125]
	v_mfma_f32_16x16x32_bf16 v[110:113], v[148:151], v[194:197], v[110:113]
	v_mfma_f32_16x16x32_bf16 v[106:109], v[156:159], v[194:197], v[106:109]
	v_mfma_f32_16x16x32_bf16 v[86:89], v[148:151], v[210:213], v[86:89]
	v_mfma_f32_16x16x32_bf16 v[82:85], v[156:159], v[210:213], v[82:85]
	v_mfma_f32_16x16x32_bf16 v[70:73], v[148:151], v[218:221], v[70:73]
	v_mfma_f32_16x16x32_bf16 v[66:69], v[156:159], v[218:221], v[66:69]
	v_mfma_f32_16x16x32_bf16 v[126:129], v[152:155], v[190:193], v[126:129]
	v_mfma_f32_16x16x32_bf16 v[122:125], v[166:169], v[190:193], v[122:125]
	v_mfma_f32_16x16x32_bf16 v[110:113], v[152:155], v[198:201], v[110:113]
	v_mfma_f32_16x16x32_bf16 v[106:109], v[166:169], v[198:201], v[106:109]
	v_mfma_f32_16x16x32_bf16 v[86:89], v[152:155], v[214:217], v[86:89]
	v_mfma_f32_16x16x32_bf16 v[82:85], v[166:169], v[214:217], v[82:85]
	v_mfma_f32_16x16x32_bf16 v[70:73], v[152:155], v[222:225], v[70:73]
	v_mfma_f32_16x16x32_bf16 v[66:69], v[166:169], v[222:225], v[66:69]
	s_setprio 0
	s_setprio 1
	v_mfma_f32_16x16x32_bf16 v[118:121], v[170:173], v[186:189], v[118:121]
	v_mfma_f32_16x16x32_bf16 v[114:117], v[178:181], v[186:189], v[114:117]
	v_mfma_f32_16x16x32_bf16 v[102:105], v[170:173], v[194:197], v[102:105]
	v_mfma_f32_16x16x32_bf16 v[98:101], v[178:181], v[194:197], v[98:101]
	v_mfma_f32_16x16x32_bf16 v[90:93], v[170:173], v[210:213], v[90:93]
	v_mfma_f32_16x16x32_bf16 v[94:97], v[178:181], v[210:213], v[94:97]
	v_mfma_f32_16x16x32_bf16 v[74:77], v[170:173], v[218:221], v[74:77]
	v_mfma_f32_16x16x32_bf16 v[78:81], v[178:181], v[218:221], v[78:81]
	v_mfma_f32_16x16x32_bf16 v[118:121], v[174:177], v[190:193], v[118:121]
	v_mfma_f32_16x16x32_bf16 v[114:117], v[182:185], v[190:193], v[114:117]
	v_mfma_f32_16x16x32_bf16 v[102:105], v[174:177], v[198:201], v[102:105]
	v_mfma_f32_16x16x32_bf16 v[98:101], v[182:185], v[198:201], v[98:101]
	v_mfma_f32_16x16x32_bf16 v[90:93], v[174:177], v[214:217], v[90:93]
	v_mfma_f32_16x16x32_bf16 v[94:97], v[182:185], v[214:217], v[94:97]
	v_mfma_f32_16x16x32_bf16 v[74:77], v[174:177], v[222:225], v[74:77]
	v_mfma_f32_16x16x32_bf16 v[78:81], v[182:185], v[222:225], v[78:81]
	s_setprio 0
	s_barrier
	s_add_i32 s20, s20, s83
	v_lshl_add_u64 v[160:161], v[160:161], 0, s[4:5]
	s_mov_b32 m0, s20
	ds_read_b128 v[186:189], v147 offset:49152
	ds_read_b128 v[190:193], v147 offset:50176
	ds_read_b128 v[194:197], v147 offset:51200
	ds_read_b128 v[198:201], v147 offset:52224
	ds_read_b128 v[210:213], v147 offset:53248
	ds_read_b128 v[214:217], v147 offset:54272
	ds_read_b128 v[218:221], v147 offset:55296
	ds_read_b128 v[222:225], v147 offset:56320
	global_load_lds_dwordx4 v[160:161], off
	v_lshl_add_u64 v[160:161], v[202:203], 0, s[4:5]
	s_add_i32 m0, s20, 0x2000
	s_add_i32 s20, s78, s83
	global_load_lds_dwordx4 v[160:161], off
	v_lshl_add_u64 v[160:161], v[206:207], 0, s[4:5]
	s_mov_b32 m0, s20
	s_nop 0
	global_load_lds_dwordx4 v[160:161], off
	v_lshl_add_u64 v[160:161], v[226:227], 0, s[4:5]
	s_add_i32 m0, s20, 0x2000
	s_nop 0
	global_load_lds_dwordx4 v[160:161], off
	v_lshl_add_u64 v[160:161], v[228:229], 0, s[4:5]
	s_mov_b32 m0, s35
	s_nop 0
	global_load_lds_dwordx4 v[160:161], off
	v_lshl_add_u64 v[160:161], v[230:231], 0, s[4:5]
	s_mov_b32 m0, s28
	s_nop 0
	global_load_lds_dwordx4 v[160:161], off
	s_waitcnt vmcnt(8)
	s_waitcnt lgkmcnt(0)
	s_barrier
	s_setprio 1
	s_waitcnt lgkmcnt(0)
	v_mfma_f32_16x16x32_bf16 v[54:57], v[148:151], v[186:189], v[54:57]
	v_mfma_f32_16x16x32_bf16 v[50:53], v[156:159], v[186:189], v[50:53]
	v_mfma_f32_16x16x32_bf16 v[38:41], v[148:151], v[194:197], v[38:41]
	v_mfma_f32_16x16x32_bf16 v[34:37], v[156:159], v[194:197], v[34:37]
	v_mfma_f32_16x16x32_bf16 v[22:25], v[148:151], v[210:213], v[22:25]
	v_mfma_f32_16x16x32_bf16 v[18:21], v[156:159], v[210:213], v[18:21]
	v_mfma_f32_16x16x32_bf16 v[6:9], v[148:151], v[218:221], v[6:9]
	v_mfma_f32_16x16x32_bf16 v[2:5], v[156:159], v[218:221], v[2:5]
	v_mfma_f32_16x16x32_bf16 v[54:57], v[152:155], v[190:193], v[54:57]
	v_mfma_f32_16x16x32_bf16 v[50:53], v[166:169], v[190:193], v[50:53]
	v_mfma_f32_16x16x32_bf16 v[38:41], v[152:155], v[198:201], v[38:41]
	v_mfma_f32_16x16x32_bf16 v[34:37], v[166:169], v[198:201], v[34:37]
	v_mfma_f32_16x16x32_bf16 v[22:25], v[152:155], v[214:217], v[22:25]
	v_mfma_f32_16x16x32_bf16 v[18:21], v[166:169], v[214:217], v[18:21]
	v_mfma_f32_16x16x32_bf16 v[6:9], v[152:155], v[222:225], v[6:9]
	v_mfma_f32_16x16x32_bf16 v[2:5], v[166:169], v[222:225], v[2:5]
	s_setprio 0
	s_setprio 1
	v_mfma_f32_16x16x32_bf16 v[58:61], v[170:173], v[186:189], v[58:61]
	v_mfma_f32_16x16x32_bf16 v[62:65], v[178:181], v[186:189], v[62:65]
	v_mfma_f32_16x16x32_bf16 v[42:45], v[170:173], v[194:197], v[42:45]
	v_mfma_f32_16x16x32_bf16 v[46:49], v[178:181], v[194:197], v[46:49]
	v_mfma_f32_16x16x32_bf16 v[26:29], v[170:173], v[210:213], v[26:29]
	v_mfma_f32_16x16x32_bf16 v[30:33], v[178:181], v[210:213], v[30:33]
	v_mfma_f32_16x16x32_bf16 v[10:13], v[170:173], v[218:221], v[10:13]
	v_mfma_f32_16x16x32_bf16 v[14:17], v[178:181], v[218:221], v[14:17]
	v_mfma_f32_16x16x32_bf16 v[58:61], v[174:177], v[190:193], v[58:61]
	v_mfma_f32_16x16x32_bf16 v[62:65], v[182:185], v[190:193], v[62:65]
	v_mfma_f32_16x16x32_bf16 v[42:45], v[174:177], v[198:201], v[42:45]
	v_mfma_f32_16x16x32_bf16 v[46:49], v[182:185], v[198:201], v[46:49]
	v_mfma_f32_16x16x32_bf16 v[26:29], v[174:177], v[214:217], v[26:29]
	v_mfma_f32_16x16x32_bf16 v[30:33], v[182:185], v[214:217], v[30:33]
	v_mfma_f32_16x16x32_bf16 v[10:13], v[174:177], v[222:225], v[10:13]
	v_mfma_f32_16x16x32_bf16 v[14:17], v[182:185], v[222:225], v[14:17]
	s_setprio 0
	s_add_u32 s94, s94, 0x100
	s_addc_u32 s95, s95, 0
	v_lshl_add_u64 v[142:143], v[142:143], 0, s[26:27]
	v_lshl_add_u64 v[140:141], v[140:141], 0, s[26:27]
	s_cmp_ge_u32 s99, s82
	s_mov_b32 s96, s99
	s_barrier
	s_cbranch_scc0 .LBB0_527
	s_and_b64 vcc, exec, s[8:9]
	s_cbranch_vccnz .LBB0_515
	v_mov_b32_e32 v14, 0
	s_mov_b32 s84, s80
	s_mov_b32 s81, s85
	s_mov_b64 s[90:91], s[92:93]
	s_mov_b64 s[88:89], s[10:11]
	s_mov_b32 s29, s98
	v_mov_b32_e32 v15, v14
	v_mov_b32_e32 v16, v14
	v_mov_b32_e32 v17, v14
	v_mov_b32_e32 v10, v14
	v_mov_b32_e32 v11, v14
	v_mov_b32_e32 v12, v14
	v_mov_b32_e32 v13, v14
	v_mov_b32_e32 v30, v14
	v_mov_b32_e32 v31, v14
	v_mov_b32_e32 v32, v14
	v_mov_b32_e32 v33, v14
	v_mov_b32_e32 v26, v14
	v_mov_b32_e32 v27, v14
	v_mov_b32_e32 v28, v14
	v_mov_b32_e32 v29, v14
	v_mov_b32_e32 v46, v14
	v_mov_b32_e32 v47, v14
	v_mov_b32_e32 v48, v14
	v_mov_b32_e32 v49, v14
	v_mov_b32_e32 v42, v14
	v_mov_b32_e32 v43, v14
	v_mov_b32_e32 v44, v14
	v_mov_b32_e32 v45, v14
	v_mov_b32_e32 v62, v14
	v_mov_b32_e32 v63, v14
	v_mov_b32_e32 v64, v14
	v_mov_b32_e32 v65, v14
	v_mov_b32_e32 v58, v14
	v_mov_b32_e32 v59, v14
	v_mov_b32_e32 v60, v14
	v_mov_b32_e32 v61, v14
	v_mov_b32_e32 v2, v14
	v_mov_b32_e32 v3, v14
	v_mov_b32_e32 v4, v14
	v_mov_b32_e32 v5, v14
	v_mov_b32_e32 v6, v14
	v_mov_b32_e32 v7, v14
	v_mov_b32_e32 v8, v14
	v_mov_b32_e32 v9, v14
	v_mov_b32_e32 v18, v14
	v_mov_b32_e32 v19, v14
	v_mov_b32_e32 v20, v14
	v_mov_b32_e32 v21, v14
	v_mov_b32_e32 v22, v14
	v_mov_b32_e32 v23, v14
	v_mov_b32_e32 v24, v14
	v_mov_b32_e32 v25, v14
	v_mov_b32_e32 v34, v14
	v_mov_b32_e32 v35, v14
	v_mov_b32_e32 v36, v14
	v_mov_b32_e32 v37, v14
	v_mov_b32_e32 v38, v14
	v_mov_b32_e32 v39, v14
	v_mov_b32_e32 v40, v14
	v_mov_b32_e32 v41, v14
	v_mov_b32_e32 v50, v14
	v_mov_b32_e32 v51, v14
	v_mov_b32_e32 v52, v14
	v_mov_b32_e32 v53, v14
	v_mov_b32_e32 v54, v14
	v_mov_b32_e32 v55, v14
	v_mov_b32_e32 v56, v14
	v_mov_b32_e32 v57, v14
	v_mov_b32_e32 v78, v14
	v_mov_b32_e32 v79, v14
	v_mov_b32_e32 v80, v14
	v_mov_b32_e32 v81, v14
	v_mov_b32_e32 v74, v14
	v_mov_b32_e32 v75, v14
	v_mov_b32_e32 v76, v14
	v_mov_b32_e32 v77, v14
	v_mov_b32_e32 v94, v14
	v_mov_b32_e32 v95, v14
	v_mov_b32_e32 v96, v14
	v_mov_b32_e32 v97, v14
	v_mov_b32_e32 v90, v14
	v_mov_b32_e32 v91, v14
	v_mov_b32_e32 v92, v14
	v_mov_b32_e32 v93, v14
	v_mov_b32_e32 v98, v14
	v_mov_b32_e32 v99, v14
	v_mov_b32_e32 v100, v14
	v_mov_b32_e32 v101, v14
	v_mov_b32_e32 v102, v14
	v_mov_b32_e32 v103, v14
	v_mov_b32_e32 v104, v14
	v_mov_b32_e32 v105, v14
	v_mov_b32_e32 v114, v14
	v_mov_b32_e32 v115, v14
	v_mov_b32_e32 v116, v14
	v_mov_b32_e32 v117, v14
	v_mov_b32_e32 v118, v14
	v_mov_b32_e32 v119, v14
	v_mov_b32_e32 v120, v14
	v_mov_b32_e32 v121, v14
	v_mov_b32_e32 v66, v14
	v_mov_b32_e32 v67, v14
	v_mov_b32_e32 v68, v14
	v_mov_b32_e32 v69, v14
	v_mov_b32_e32 v70, v14
	v_mov_b32_e32 v71, v14
	v_mov_b32_e32 v72, v14
	v_mov_b32_e32 v73, v14
	v_mov_b32_e32 v82, v14
	v_mov_b32_e32 v83, v14
	v_mov_b32_e32 v84, v14
	v_mov_b32_e32 v85, v14
	v_mov_b32_e32 v86, v14
	v_mov_b32_e32 v87, v14
	v_mov_b32_e32 v88, v14
	v_mov_b32_e32 v89, v14
	v_mov_b32_e32 v106, v14
	v_mov_b32_e32 v107, v14
	v_mov_b32_e32 v108, v14
	v_mov_b32_e32 v109, v14
	v_mov_b32_e32 v110, v14
	v_mov_b32_e32 v111, v14
	v_mov_b32_e32 v112, v14
	v_mov_b32_e32 v113, v14
	v_mov_b32_e32 v122, v14
	v_mov_b32_e32 v123, v14
	v_mov_b32_e32 v124, v14
	v_mov_b32_e32 v125, v14
	v_mov_b32_e32 v126, v14
	v_mov_b32_e32 v127, v14
	v_mov_b32_e32 v128, v14
	v_mov_b32_e32 v129, v14
	s_branch .LBB0_515

.LBB0_660:
	s_add_i32 s54, s36, 2
	s_add_u32 s55, s28, 0x80
	s_addc_u32 s37, s29, 0
	s_add_i32 s58, 0, 0x10000
	s_cmp_eq_u32 s50, s36
	s_cselect_b32 s37, s9, s37
	s_cselect_b32 s36, s8, s55
	v_add_u32_e32 v144, s58, v147
	s_cselect_b32 s57, s25, s35
	s_cselect_b32 s56, s24, s34
	s_add_i32 s55, 0, 0x14000
	ds_read_b128 v[140:143], v144
	ds_read_b128 v[150:153], v144 offset:1024
	ds_read_b128 v[154:157], v144 offset:2048
	ds_read_b128 v[158:161], v144 offset:3072
	v_add_u32_e32 v144, s55, v147
	ds_read_b128 v[166:169], v144
	ds_read_b128 v[170:173], v144 offset:1024
	ds_read_b128 v[174:177], v144 offset:2048
	ds_read_b128 v[178:181], v144 offset:3072
	v_lshl_add_u64 v[144:145], s[28:29], 0, v[136:137]
	s_add_i32 m0, s40, 0xc000
	ds_read_b128 v[182:185], v149
	ds_read_b128 v[186:189], v149 offset:1024
	ds_read_b128 v[190:193], v149 offset:2048
	ds_read_b128 v[194:197], v149 offset:3072
	ds_read_b128 v[198:201], v149 offset:4096
	ds_read_b128 v[210:213], v149 offset:5120
	ds_read_b128 v[214:217], v149 offset:6144
	ds_read_b128 v[218:221], v149 offset:7168
	global_load_lds_dwordx4 v[144:145], off
	v_lshl_add_u64 v[144:145], s[28:29], 0, v[138:139]
	s_add_i32 m0, s40, 0xe000
	s_nop 0
	global_load_lds_dwordx4 v[144:145], off
	s_waitcnt vmcnt(8)
	s_waitcnt lgkmcnt(0)
	s_barrier
	s_setprio 1
	s_waitcnt lgkmcnt(0)
	v_mfma_f32_16x16x32_bf16 v[126:129], v[140:143], v[182:185], v[126:129]
	v_mfma_f32_16x16x32_bf16 v[122:125], v[154:157], v[182:185], v[122:125]
	v_mfma_f32_16x16x32_bf16 v[110:113], v[140:143], v[190:193], v[110:113]
	v_mfma_f32_16x16x32_bf16 v[106:109], v[154:157], v[190:193], v[106:109]
	v_mfma_f32_16x16x32_bf16 v[94:97], v[140:143], v[198:201], v[94:97]
	v_mfma_f32_16x16x32_bf16 v[90:93], v[154:157], v[198:201], v[90:93]
	v_mfma_f32_16x16x32_bf16 v[78:81], v[140:143], v[214:217], v[78:81]
	v_mfma_f32_16x16x32_bf16 v[74:77], v[154:157], v[214:217], v[74:77]
	v_mfma_f32_16x16x32_bf16 v[126:129], v[150:153], v[186:189], v[126:129]
	v_mfma_f32_16x16x32_bf16 v[122:125], v[158:161], v[186:189], v[122:125]
	v_mfma_f32_16x16x32_bf16 v[110:113], v[150:153], v[194:197], v[110:113]
	v_mfma_f32_16x16x32_bf16 v[106:109], v[158:161], v[194:197], v[106:109]
	v_mfma_f32_16x16x32_bf16 v[94:97], v[150:153], v[210:213], v[94:97]
	v_mfma_f32_16x16x32_bf16 v[90:93], v[158:161], v[210:213], v[90:93]
	v_mfma_f32_16x16x32_bf16 v[78:81], v[150:153], v[218:221], v[78:81]
	v_mfma_f32_16x16x32_bf16 v[74:77], v[158:161], v[218:221], v[74:77]
	s_setprio 0
	s_setprio 1
	v_mfma_f32_16x16x32_bf16 v[118:121], v[166:169], v[182:185], v[118:121]
	v_mfma_f32_16x16x32_bf16 v[114:117], v[174:177], v[182:185], v[114:117]
	v_mfma_f32_16x16x32_bf16 v[102:105], v[166:169], v[190:193], v[102:105]
	v_mfma_f32_16x16x32_bf16 v[98:101], v[174:177], v[190:193], v[98:101]
	v_mfma_f32_16x16x32_bf16 v[86:89], v[166:169], v[198:201], v[86:89]
	v_mfma_f32_16x16x32_bf16 v[82:85], v[174:177], v[198:201], v[82:85]
	v_mfma_f32_16x16x32_bf16 v[70:73], v[166:169], v[214:217], v[70:73]
	v_mfma_f32_16x16x32_bf16 v[66:69], v[174:177], v[214:217], v[66:69]
	v_mfma_f32_16x16x32_bf16 v[118:121], v[170:173], v[186:189], v[118:121]
	v_mfma_f32_16x16x32_bf16 v[114:117], v[178:181], v[186:189], v[114:117]
	v_mfma_f32_16x16x32_bf16 v[102:105], v[170:173], v[194:197], v[102:105]
	v_mfma_f32_16x16x32_bf16 v[98:101], v[178:181], v[194:197], v[98:101]
	v_mfma_f32_16x16x32_bf16 v[86:89], v[170:173], v[210:213], v[86:89]
	v_mfma_f32_16x16x32_bf16 v[82:85], v[178:181], v[210:213], v[82:85]
	v_mfma_f32_16x16x32_bf16 v[70:73], v[170:173], v[218:221], v[70:73]
	v_mfma_f32_16x16x32_bf16 v[66:69], v[178:181], v[218:221], v[66:69]
	s_setprio 0
	s_barrier
	s_add_i32 s58, s58, s39
	v_lshl_add_u64 v[144:145], s[56:57], 0, v[0:1]
	s_mov_b32 m0, s58
	ds_read_b128 v[182:185], v149 offset:16384
	ds_read_b128 v[186:189], v149 offset:17408
	ds_read_b128 v[190:193], v149 offset:18432
	ds_read_b128 v[194:197], v149 offset:19456
	ds_read_b128 v[198:201], v149 offset:20480
	ds_read_b128 v[210:213], v149 offset:21504
	ds_read_b128 v[214:217], v149 offset:22528
	ds_read_b128 v[218:221], v149 offset:23552
	global_load_lds_dwordx4 v[144:145], off
	s_add_i32 m0, s58, 0x2000
	v_lshl_add_u64 v[202:203], s[56:57], 0, v[130:131]
	s_add_u32 s56, s56, s0
	s_addc_u32 s57, s57, 0
	s_add_i32 s55, s55, s39
	global_load_lds_dwordx4 v[202:203], off
	v_lshl_add_u64 v[206:207], s[56:57], 0, v[0:1]
	s_mov_b32 m0, s55
	v_lshl_add_u64 v[222:223], s[56:57], 0, v[130:131]
	global_load_lds_dwordx4 v[206:207], off
	s_add_i32 m0, s55, 0x2000
	v_lshl_add_u64 v[224:225], s[36:37], 0, v[134:135]
	global_load_lds_dwordx4 v[222:223], off
	s_mov_b32 m0, s40
	v_lshl_add_u64 v[226:227], s[36:37], 0, v[132:133]
	global_load_lds_dwordx4 v[224:225], off
	s_mov_b32 m0, s41
	s_nop 0
	global_load_lds_dwordx4 v[226:227], off
	s_waitcnt vmcnt(8)
	s_waitcnt lgkmcnt(0)
	s_barrier
	s_setprio 1
	s_waitcnt lgkmcnt(0)
	v_mfma_f32_16x16x32_bf16 v[62:65], v[140:143], v[182:185], v[62:65]
	v_mfma_f32_16x16x32_bf16 v[58:61], v[154:157], v[182:185], v[58:61]
	v_mfma_f32_16x16x32_bf16 v[46:49], v[140:143], v[190:193], v[46:49]
	v_mfma_f32_16x16x32_bf16 v[42:45], v[154:157], v[190:193], v[42:45]
	v_mfma_f32_16x16x32_bf16 v[30:33], v[140:143], v[198:201], v[30:33]
	v_mfma_f32_16x16x32_bf16 v[26:29], v[154:157], v[198:201], v[26:29]
	v_mfma_f32_16x16x32_bf16 v[14:17], v[140:143], v[214:217], v[14:17]
	v_mfma_f32_16x16x32_bf16 v[10:13], v[154:157], v[214:217], v[10:13]
	v_mfma_f32_16x16x32_bf16 v[62:65], v[150:153], v[186:189], v[62:65]
	v_mfma_f32_16x16x32_bf16 v[58:61], v[158:161], v[186:189], v[58:61]
	v_mfma_f32_16x16x32_bf16 v[46:49], v[150:153], v[194:197], v[46:49]
	v_mfma_f32_16x16x32_bf16 v[42:45], v[158:161], v[194:197], v[42:45]
	v_mfma_f32_16x16x32_bf16 v[30:33], v[150:153], v[210:213], v[30:33]
	v_mfma_f32_16x16x32_bf16 v[26:29], v[158:161], v[210:213], v[26:29]
	v_mfma_f32_16x16x32_bf16 v[14:17], v[150:153], v[218:221], v[14:17]
	v_mfma_f32_16x16x32_bf16 v[10:13], v[158:161], v[218:221], v[10:13]
	s_setprio 0
	s_setprio 1
	v_mfma_f32_16x16x32_bf16 v[54:57], v[166:169], v[182:185], v[54:57]
	v_mfma_f32_16x16x32_bf16 v[50:53], v[174:177], v[182:185], v[50:53]
	v_mfma_f32_16x16x32_bf16 v[38:41], v[166:169], v[190:193], v[38:41]
	v_mfma_f32_16x16x32_bf16 v[34:37], v[174:177], v[190:193], v[34:37]
	v_mfma_f32_16x16x32_bf16 v[22:25], v[166:169], v[198:201], v[22:25]
	v_mfma_f32_16x16x32_bf16 v[18:21], v[174:177], v[198:201], v[18:21]
	v_mfma_f32_16x16x32_bf16 v[6:9], v[166:169], v[214:217], v[6:9]
	v_mfma_f32_16x16x32_bf16 v[2:5], v[174:177], v[214:217], v[2:5]
	v_mfma_f32_16x16x32_bf16 v[54:57], v[170:173], v[186:189], v[54:57]
	v_mfma_f32_16x16x32_bf16 v[50:53], v[178:181], v[186:189], v[50:53]
	v_mfma_f32_16x16x32_bf16 v[38:41], v[170:173], v[194:197], v[38:41]
	v_mfma_f32_16x16x32_bf16 v[34:37], v[178:181], v[194:197], v[34:37]
	v_mfma_f32_16x16x32_bf16 v[22:25], v[170:173], v[210:213], v[22:25]
	v_mfma_f32_16x16x32_bf16 v[18:21], v[178:181], v[210:213], v[18:21]
	v_mfma_f32_16x16x32_bf16 v[6:9], v[170:173], v[218:221], v[6:9]
	v_mfma_f32_16x16x32_bf16 v[2:5], v[178:181], v[218:221], v[2:5]
	s_setprio 0
	s_barrier
	s_add_i32 s55, 0, 0x18000
	s_add_i32 s56, 0, 0x1c000
	v_add_u32_e32 v158, s55, v147
	v_add_u32_e32 v178, s56, v147
	ds_read_b128 v[140:143], v158
	ds_read_b128 v[150:153], v158 offset:1024
	ds_read_b128 v[154:157], v158 offset:2048
	ds_read_b128 v[158:161], v158 offset:3072
	ds_read_b128 v[166:169], v178
	ds_read_b128 v[170:173], v178 offset:1024
	ds_read_b128 v[174:177], v178 offset:2048
	ds_read_b128 v[178:181], v178 offset:3072
	s_add_u32 s36, s36, s0
	s_addc_u32 s37, s37, 0
	s_mov_b32 m0, s42
	v_lshl_add_u64 v[228:229], s[36:37], 0, v[134:135]
	ds_read_b128 v[182:185], v149 offset:32768
	ds_read_b128 v[186:189], v149 offset:33792
	ds_read_b128 v[190:193], v149 offset:34816
	ds_read_b128 v[194:197], v149 offset:35840
	ds_read_b128 v[198:201], v149 offset:36864
	ds_read_b128 v[210:213], v149 offset:37888
	ds_read_b128 v[214:217], v149 offset:38912
	ds_read_b128 v[218:221], v149 offset:39936
	global_load_lds_dwordx4 v[228:229], off
	v_lshl_add_u64 v[228:229], s[36:37], 0, v[132:133]
	s_mov_b32 m0, s43
	s_nop 0
	global_load_lds_dwordx4 v[228:229], off
	s_waitcnt vmcnt(8)
	s_waitcnt lgkmcnt(0)
	s_barrier
	s_setprio 1
	s_waitcnt lgkmcnt(0)
	v_mfma_f32_16x16x32_bf16 v[126:129], v[140:143], v[182:185], v[126:129]
	v_mfma_f32_16x16x32_bf16 v[122:125], v[154:157], v[182:185], v[122:125]
	v_mfma_f32_16x16x32_bf16 v[110:113], v[140:143], v[190:193], v[110:113]
	v_mfma_f32_16x16x32_bf16 v[106:109], v[154:157], v[190:193], v[106:109]
	v_mfma_f32_16x16x32_bf16 v[94:97], v[140:143], v[198:201], v[94:97]
	v_mfma_f32_16x16x32_bf16 v[90:93], v[154:157], v[198:201], v[90:93]
	v_mfma_f32_16x16x32_bf16 v[78:81], v[140:143], v[214:217], v[78:81]
	v_mfma_f32_16x16x32_bf16 v[74:77], v[154:157], v[214:217], v[74:77]
	v_mfma_f32_16x16x32_bf16 v[126:129], v[150:153], v[186:189], v[126:129]
	v_mfma_f32_16x16x32_bf16 v[122:125], v[158:161], v[186:189], v[122:125]
	v_mfma_f32_16x16x32_bf16 v[110:113], v[150:153], v[194:197], v[110:113]
	v_mfma_f32_16x16x32_bf16 v[106:109], v[158:161], v[194:197], v[106:109]
	v_mfma_f32_16x16x32_bf16 v[94:97], v[150:153], v[210:213], v[94:97]
	v_mfma_f32_16x16x32_bf16 v[90:93], v[158:161], v[210:213], v[90:93]
	v_mfma_f32_16x16x32_bf16 v[78:81], v[150:153], v[218:221], v[78:81]
	v_mfma_f32_16x16x32_bf16 v[74:77], v[158:161], v[218:221], v[74:77]
	s_setprio 0
	s_setprio 1
	v_mfma_f32_16x16x32_bf16 v[118:121], v[166:169], v[182:185], v[118:121]
	v_mfma_f32_16x16x32_bf16 v[114:117], v[174:177], v[182:185], v[114:117]
	v_mfma_f32_16x16x32_bf16 v[102:105], v[166:169], v[190:193], v[102:105]
	v_mfma_f32_16x16x32_bf16 v[98:101], v[174:177], v[190:193], v[98:101]
	v_mfma_f32_16x16x32_bf16 v[86:89], v[166:169], v[198:201], v[86:89]
	v_mfma_f32_16x16x32_bf16 v[82:85], v[174:177], v[198:201], v[82:85]
	v_mfma_f32_16x16x32_bf16 v[70:73], v[166:169], v[214:217], v[70:73]
	v_mfma_f32_16x16x32_bf16 v[66:69], v[174:177], v[214:217], v[66:69]
	v_mfma_f32_16x16x32_bf16 v[118:121], v[170:173], v[186:189], v[118:121]
	v_mfma_f32_16x16x32_bf16 v[114:117], v[178:181], v[186:189], v[114:117]
	v_mfma_f32_16x16x32_bf16 v[102:105], v[170:173], v[194:197], v[102:105]
	v_mfma_f32_16x16x32_bf16 v[98:101], v[178:181], v[194:197], v[98:101]
	v_mfma_f32_16x16x32_bf16 v[86:89], v[170:173], v[210:213], v[86:89]
	v_mfma_f32_16x16x32_bf16 v[82:85], v[178:181], v[210:213], v[82:85]
	v_mfma_f32_16x16x32_bf16 v[70:73], v[170:173], v[218:221], v[70:73]
	v_mfma_f32_16x16x32_bf16 v[66:69], v[178:181], v[218:221], v[66:69]
	s_setprio 0
	s_barrier
	s_add_i32 s36, s55, s39
	v_lshl_add_u64 v[144:145], v[144:145], 0, s[4:5]
	s_mov_b32 m0, s36
	ds_read_b128 v[182:185], v149 offset:49152
	ds_read_b128 v[186:189], v149 offset:50176
	ds_read_b128 v[190:193], v149 offset:51200
	ds_read_b128 v[194:197], v149 offset:52224
	ds_read_b128 v[198:201], v149 offset:53248
	ds_read_b128 v[210:213], v149 offset:54272
	ds_read_b128 v[214:217], v149 offset:55296
	ds_read_b128 v[218:221], v149 offset:56320
	global_load_lds_dwordx4 v[144:145], off
	v_lshl_add_u64 v[144:145], v[202:203], 0, s[4:5]
	s_add_i32 m0, s36, 0x2000
	s_add_i32 s36, s56, s39
	global_load_lds_dwordx4 v[144:145], off
	v_lshl_add_u64 v[144:145], v[206:207], 0, s[4:5]
	s_mov_b32 m0, s36
	s_nop 0
	global_load_lds_dwordx4 v[144:145], off
	v_lshl_add_u64 v[144:145], v[222:223], 0, s[4:5]
	s_add_i32 m0, s36, 0x2000
	s_nop 0
	global_load_lds_dwordx4 v[144:145], off
	v_lshl_add_u64 v[144:145], v[224:225], 0, s[4:5]
	s_mov_b32 m0, s48
	s_nop 0
	global_load_lds_dwordx4 v[144:145], off
	v_lshl_add_u64 v[144:145], v[226:227], 0, s[4:5]
	s_mov_b32 m0, s49
	s_nop 0
	global_load_lds_dwordx4 v[144:145], off
	s_waitcnt vmcnt(8)
	s_waitcnt lgkmcnt(0)
	s_barrier
	s_setprio 1
	s_waitcnt lgkmcnt(0)
	v_mfma_f32_16x16x32_bf16 v[62:65], v[140:143], v[182:185], v[62:65]
	v_mfma_f32_16x16x32_bf16 v[58:61], v[154:157], v[182:185], v[58:61]
	v_mfma_f32_16x16x32_bf16 v[46:49], v[140:143], v[190:193], v[46:49]
	v_mfma_f32_16x16x32_bf16 v[42:45], v[154:157], v[190:193], v[42:45]
	v_mfma_f32_16x16x32_bf16 v[30:33], v[140:143], v[198:201], v[30:33]
	v_mfma_f32_16x16x32_bf16 v[26:29], v[154:157], v[198:201], v[26:29]
	v_mfma_f32_16x16x32_bf16 v[14:17], v[140:143], v[214:217], v[14:17]
	v_mfma_f32_16x16x32_bf16 v[10:13], v[154:157], v[214:217], v[10:13]
	v_mfma_f32_16x16x32_bf16 v[62:65], v[150:153], v[186:189], v[62:65]
	v_mfma_f32_16x16x32_bf16 v[58:61], v[158:161], v[186:189], v[58:61]
	v_mfma_f32_16x16x32_bf16 v[46:49], v[150:153], v[194:197], v[46:49]
	v_mfma_f32_16x16x32_bf16 v[42:45], v[158:161], v[194:197], v[42:45]
	v_mfma_f32_16x16x32_bf16 v[30:33], v[150:153], v[210:213], v[30:33]
	v_mfma_f32_16x16x32_bf16 v[26:29], v[158:161], v[210:213], v[26:29]
	v_mfma_f32_16x16x32_bf16 v[14:17], v[150:153], v[218:221], v[14:17]
	v_mfma_f32_16x16x32_bf16 v[10:13], v[158:161], v[218:221], v[10:13]
	s_setprio 0
	s_setprio 1
	v_mfma_f32_16x16x32_bf16 v[54:57], v[166:169], v[182:185], v[54:57]
	v_mfma_f32_16x16x32_bf16 v[50:53], v[174:177], v[182:185], v[50:53]
	v_mfma_f32_16x16x32_bf16 v[38:41], v[166:169], v[190:193], v[38:41]
	v_mfma_f32_16x16x32_bf16 v[34:37], v[174:177], v[190:193], v[34:37]
	v_mfma_f32_16x16x32_bf16 v[22:25], v[166:169], v[198:201], v[22:25]
	v_mfma_f32_16x16x32_bf16 v[18:21], v[174:177], v[198:201], v[18:21]
	v_mfma_f32_16x16x32_bf16 v[6:9], v[166:169], v[214:217], v[6:9]
	v_mfma_f32_16x16x32_bf16 v[2:5], v[174:177], v[214:217], v[2:5]
	v_mfma_f32_16x16x32_bf16 v[54:57], v[170:173], v[186:189], v[54:57]
	v_mfma_f32_16x16x32_bf16 v[50:53], v[178:181], v[186:189], v[50:53]
	v_mfma_f32_16x16x32_bf16 v[38:41], v[170:173], v[194:197], v[38:41]
	v_mfma_f32_16x16x32_bf16 v[34:37], v[178:181], v[194:197], v[34:37]
	v_mfma_f32_16x16x32_bf16 v[22:25], v[170:173], v[210:213], v[22:25]
	v_mfma_f32_16x16x32_bf16 v[18:21], v[178:181], v[210:213], v[18:21]
	v_mfma_f32_16x16x32_bf16 v[6:9], v[170:173], v[218:221], v[6:9]
	v_mfma_f32_16x16x32_bf16 v[2:5], v[178:181], v[218:221], v[2:5]
	s_setprio 0
	s_add_u32 s28, s28, 0x100
	s_addc_u32 s29, s29, 0
	s_add_u32 s34, s34, 0x100
	s_addc_u32 s35, s35, 0
	s_cmp_ge_u32 s54, s47
	s_mov_b32 s36, s54
	s_barrier
	s_cbranch_scc0 .LBB0_660
	s_and_b64 vcc, exec, s[20:21]
	s_cbranch_vccz .LBB0_663
	s_barrier

.LBB0_684:
	s_add_u32 s22, s20, 0xfffc0080
	s_addc_u32 s23, s21, -1
	s_add_i32 s51, 0, 0x10000
	s_cmp_eq_u32 s50, 12
	s_cselect_b32 s25, s15, s23
	s_cselect_b32 s24, s43, s22
	v_add_u32_e32 v140, s51, v143
	s_cselect_b32 s23, s13, s49
	s_cselect_b32 s22, s47, s48
	s_add_i32 s54, 0, 0x14000
	ds_read_b128 v[146:149], v140
	ds_read_b128 v[150:153], v140 offset:1024
	ds_read_b128 v[154:157], v140 offset:2048
	ds_read_b128 v[158:161], v140 offset:3072
	v_add_u32_e32 v140, s54, v143
	ds_read_b128 v[166:169], v140
	ds_read_b128 v[170:173], v140 offset:1024
	ds_read_b128 v[174:177], v140 offset:2048
	ds_read_b128 v[178:181], v140 offset:3072
	v_lshl_add_u64 v[140:141], s[20:21], 0, v[136:137]
	s_add_i32 m0, s36, 0xc000
	ds_read_b128 v[182:185], v145
	ds_read_b128 v[186:189], v145 offset:1024
	ds_read_b128 v[190:193], v145 offset:2048
	ds_read_b128 v[194:197], v145 offset:3072
	ds_read_b128 v[198:201], v145 offset:4096
	ds_read_b128 v[210:213], v145 offset:5120
	ds_read_b128 v[214:217], v145 offset:6144
	ds_read_b128 v[218:221], v145 offset:7168
	global_load_lds_dwordx4 v[140:141], off
	v_lshl_add_u64 v[140:141], s[20:21], 0, v[138:139]
	s_add_i32 m0, s36, 0xe000
	s_nop 0
	global_load_lds_dwordx4 v[140:141], off
	s_waitcnt vmcnt(8)
	s_waitcnt lgkmcnt(0)
	s_barrier
	s_setprio 1
	s_waitcnt lgkmcnt(0)
	v_mfma_f32_16x16x32_bf16 v[126:129], v[146:149], v[182:185], v[126:129]
	v_mfma_f32_16x16x32_bf16 v[118:121], v[154:157], v[182:185], v[118:121]
	v_mfma_f32_16x16x32_bf16 v[110:113], v[146:149], v[190:193], v[110:113]
	v_mfma_f32_16x16x32_bf16 v[102:105], v[154:157], v[190:193], v[102:105]
	v_mfma_f32_16x16x32_bf16 v[94:97], v[146:149], v[198:201], v[94:97]
	v_mfma_f32_16x16x32_bf16 v[86:89], v[154:157], v[198:201], v[86:89]
	v_mfma_f32_16x16x32_bf16 v[78:81], v[146:149], v[214:217], v[78:81]
	v_mfma_f32_16x16x32_bf16 v[70:73], v[154:157], v[214:217], v[70:73]
	v_mfma_f32_16x16x32_bf16 v[126:129], v[150:153], v[186:189], v[126:129]
	v_mfma_f32_16x16x32_bf16 v[118:121], v[158:161], v[186:189], v[118:121]
	v_mfma_f32_16x16x32_bf16 v[110:113], v[150:153], v[194:197], v[110:113]
	v_mfma_f32_16x16x32_bf16 v[102:105], v[158:161], v[194:197], v[102:105]
	v_mfma_f32_16x16x32_bf16 v[94:97], v[150:153], v[210:213], v[94:97]
	v_mfma_f32_16x16x32_bf16 v[86:89], v[158:161], v[210:213], v[86:89]
	v_mfma_f32_16x16x32_bf16 v[78:81], v[150:153], v[218:221], v[78:81]
	v_mfma_f32_16x16x32_bf16 v[70:73], v[158:161], v[218:221], v[70:73]
	s_setprio 0
	s_setprio 1
	v_mfma_f32_16x16x32_bf16 v[122:125], v[166:169], v[182:185], v[122:125]
	v_mfma_f32_16x16x32_bf16 v[114:117], v[174:177], v[182:185], v[114:117]
	v_mfma_f32_16x16x32_bf16 v[106:109], v[166:169], v[190:193], v[106:109]
	v_mfma_f32_16x16x32_bf16 v[98:101], v[174:177], v[190:193], v[98:101]
	v_mfma_f32_16x16x32_bf16 v[90:93], v[166:169], v[198:201], v[90:93]
	v_mfma_f32_16x16x32_bf16 v[82:85], v[174:177], v[198:201], v[82:85]
	v_mfma_f32_16x16x32_bf16 v[74:77], v[166:169], v[214:217], v[74:77]
	v_mfma_f32_16x16x32_bf16 v[66:69], v[174:177], v[214:217], v[66:69]
	v_mfma_f32_16x16x32_bf16 v[122:125], v[170:173], v[186:189], v[122:125]
	v_mfma_f32_16x16x32_bf16 v[114:117], v[178:181], v[186:189], v[114:117]
	v_mfma_f32_16x16x32_bf16 v[106:109], v[170:173], v[194:197], v[106:109]
	v_mfma_f32_16x16x32_bf16 v[98:101], v[178:181], v[194:197], v[98:101]
	v_mfma_f32_16x16x32_bf16 v[90:93], v[170:173], v[210:213], v[90:93]
	v_mfma_f32_16x16x32_bf16 v[82:85], v[178:181], v[210:213], v[82:85]
	v_mfma_f32_16x16x32_bf16 v[74:77], v[170:173], v[218:221], v[74:77]
	v_mfma_f32_16x16x32_bf16 v[66:69], v[178:181], v[218:221], v[66:69]
	s_setprio 0
	s_barrier
	s_add_i32 s51, s51, s29
	v_lshl_add_u64 v[140:141], s[22:23], 0, v[0:1]
	s_mov_b32 m0, s51
	ds_read_b128 v[182:185], v145 offset:16384
	ds_read_b128 v[186:189], v145 offset:17408
	ds_read_b128 v[190:193], v145 offset:18432
	ds_read_b128 v[194:197], v145 offset:19456
	ds_read_b128 v[198:201], v145 offset:20480
	ds_read_b128 v[210:213], v145 offset:21504
	ds_read_b128 v[214:217], v145 offset:22528
	ds_read_b128 v[218:221], v145 offset:23552
	global_load_lds_dwordx4 v[140:141], off
	s_add_i32 m0, s51, 0x2000
	s_add_u32 s52, s22, 0x40000
	v_lshl_add_u64 v[202:203], s[22:23], 0, v[130:131]
	s_addc_u32 s53, s23, 0
	s_add_i32 s51, s54, s29
	global_load_lds_dwordx4 v[202:203], off
	v_lshl_add_u64 v[206:207], s[52:53], 0, v[0:1]
	s_mov_b32 m0, s51
	v_lshl_add_u64 v[222:223], s[24:25], 0, v[132:133]
	global_load_lds_dwordx4 v[206:207], off
	v_lshl_add_u64 v[206:207], s[52:53], 0, v[130:131]
	s_add_i32 m0, s51, 0x2000
	s_nop 0
	global_load_lds_dwordx4 v[206:207], off
	v_lshl_add_u64 v[206:207], s[24:25], 0, v[134:135]
	s_mov_b32 m0, s36
	s_nop 0
	global_load_lds_dwordx4 v[206:207], off
	s_mov_b32 m0, s37
	s_nop 0
	global_load_lds_dwordx4 v[222:223], off
	s_waitcnt vmcnt(8)
	s_waitcnt lgkmcnt(0)
	s_barrier
	s_setprio 1
	s_waitcnt lgkmcnt(0)
	v_mfma_f32_16x16x32_bf16 v[62:65], v[146:149], v[182:185], v[62:65]
	v_mfma_f32_16x16x32_bf16 v[54:57], v[154:157], v[182:185], v[54:57]
	v_mfma_f32_16x16x32_bf16 v[46:49], v[146:149], v[190:193], v[46:49]
	v_mfma_f32_16x16x32_bf16 v[38:41], v[154:157], v[190:193], v[38:41]
	v_mfma_f32_16x16x32_bf16 v[30:33], v[146:149], v[198:201], v[30:33]
	v_mfma_f32_16x16x32_bf16 v[22:25], v[154:157], v[198:201], v[22:25]
	v_mfma_f32_16x16x32_bf16 v[14:17], v[146:149], v[214:217], v[14:17]
	v_mfma_f32_16x16x32_bf16 v[6:9], v[154:157], v[214:217], v[6:9]
	v_mfma_f32_16x16x32_bf16 v[62:65], v[150:153], v[186:189], v[62:65]
	v_mfma_f32_16x16x32_bf16 v[54:57], v[158:161], v[186:189], v[54:57]
	v_mfma_f32_16x16x32_bf16 v[46:49], v[150:153], v[194:197], v[46:49]
	v_mfma_f32_16x16x32_bf16 v[38:41], v[158:161], v[194:197], v[38:41]
	v_mfma_f32_16x16x32_bf16 v[30:33], v[150:153], v[210:213], v[30:33]
	v_mfma_f32_16x16x32_bf16 v[22:25], v[158:161], v[210:213], v[22:25]
	v_mfma_f32_16x16x32_bf16 v[14:17], v[150:153], v[218:221], v[14:17]
	v_mfma_f32_16x16x32_bf16 v[6:9], v[158:161], v[218:221], v[6:9]
	s_setprio 0
	s_setprio 1
	v_mfma_f32_16x16x32_bf16 v[58:61], v[166:169], v[182:185], v[58:61]
	v_mfma_f32_16x16x32_bf16 v[50:53], v[174:177], v[182:185], v[50:53]
	v_mfma_f32_16x16x32_bf16 v[42:45], v[166:169], v[190:193], v[42:45]
	v_mfma_f32_16x16x32_bf16 v[34:37], v[174:177], v[190:193], v[34:37]
	v_mfma_f32_16x16x32_bf16 v[26:29], v[166:169], v[198:201], v[26:29]
	v_mfma_f32_16x16x32_bf16 v[18:21], v[174:177], v[198:201], v[18:21]
	v_mfma_f32_16x16x32_bf16 v[10:13], v[166:169], v[214:217], v[10:13]
	v_mfma_f32_16x16x32_bf16 v[2:5], v[174:177], v[214:217], v[2:5]
	v_mfma_f32_16x16x32_bf16 v[58:61], v[170:173], v[186:189], v[58:61]
	v_mfma_f32_16x16x32_bf16 v[50:53], v[178:181], v[186:189], v[50:53]
	v_mfma_f32_16x16x32_bf16 v[42:45], v[170:173], v[194:197], v[42:45]
	v_mfma_f32_16x16x32_bf16 v[34:37], v[178:181], v[194:197], v[34:37]
	v_mfma_f32_16x16x32_bf16 v[26:29], v[170:173], v[210:213], v[26:29]
	v_mfma_f32_16x16x32_bf16 v[18:21], v[178:181], v[210:213], v[18:21]
	v_mfma_f32_16x16x32_bf16 v[10:13], v[170:173], v[218:221], v[10:13]
	v_mfma_f32_16x16x32_bf16 v[2:5], v[178:181], v[218:221], v[2:5]
	s_setprio 0
	s_barrier
	s_add_i32 s51, 0, 0x18000
	s_add_i32 s52, 0, 0x1c000
	v_add_u32_e32 v158, s51, v143
	v_add_u32_e32 v178, s52, v143
	ds_read_b128 v[146:149], v158
	ds_read_b128 v[150:153], v158 offset:1024
	ds_read_b128 v[154:157], v158 offset:2048
	ds_read_b128 v[158:161], v158 offset:3072
	ds_read_b128 v[166:169], v178
	ds_read_b128 v[170:173], v178 offset:1024
	ds_read_b128 v[174:177], v178 offset:2048
	ds_read_b128 v[178:181], v178 offset:3072
	s_add_u32 s24, s24, 0x40000
	s_addc_u32 s25, s25, 0
	s_mov_b32 m0, s38
	v_lshl_add_u64 v[224:225], s[24:25], 0, v[134:135]
	ds_read_b128 v[182:185], v145 offset:32768
	ds_read_b128 v[186:189], v145 offset:33792
	ds_read_b128 v[190:193], v145 offset:34816
	ds_read_b128 v[194:197], v145 offset:35840
	ds_read_b128 v[198:201], v145 offset:36864
	ds_read_b128 v[210:213], v145 offset:37888
	ds_read_b128 v[214:217], v145 offset:38912
	ds_read_b128 v[218:221], v145 offset:39936
	global_load_lds_dwordx4 v[224:225], off
	v_lshl_add_u64 v[224:225], s[24:25], 0, v[132:133]
	s_mov_b32 m0, s39
	s_nop 0
	global_load_lds_dwordx4 v[224:225], off
	s_waitcnt vmcnt(8)
	s_waitcnt lgkmcnt(0)
	s_barrier
	s_setprio 1
	s_waitcnt lgkmcnt(0)
	v_mfma_f32_16x16x32_bf16 v[126:129], v[146:149], v[182:185], v[126:129]
	v_mfma_f32_16x16x32_bf16 v[118:121], v[154:157], v[182:185], v[118:121]
	v_mfma_f32_16x16x32_bf16 v[110:113], v[146:149], v[190:193], v[110:113]
	v_mfma_f32_16x16x32_bf16 v[102:105], v[154:157], v[190:193], v[102:105]
	v_mfma_f32_16x16x32_bf16 v[94:97], v[146:149], v[198:201], v[94:97]
	v_mfma_f32_16x16x32_bf16 v[86:89], v[154:157], v[198:201], v[86:89]
	v_mfma_f32_16x16x32_bf16 v[78:81], v[146:149], v[214:217], v[78:81]
	v_mfma_f32_16x16x32_bf16 v[70:73], v[154:157], v[214:217], v[70:73]
	v_mfma_f32_16x16x32_bf16 v[126:129], v[150:153], v[186:189], v[126:129]
	v_mfma_f32_16x16x32_bf16 v[118:121], v[158:161], v[186:189], v[118:121]
	v_mfma_f32_16x16x32_bf16 v[110:113], v[150:153], v[194:197], v[110:113]
	v_mfma_f32_16x16x32_bf16 v[102:105], v[158:161], v[194:197], v[102:105]
	v_mfma_f32_16x16x32_bf16 v[94:97], v[150:153], v[210:213], v[94:97]
	v_mfma_f32_16x16x32_bf16 v[86:89], v[158:161], v[210:213], v[86:89]
	v_mfma_f32_16x16x32_bf16 v[78:81], v[150:153], v[218:221], v[78:81]
	v_mfma_f32_16x16x32_bf16 v[70:73], v[158:161], v[218:221], v[70:73]
	s_setprio 0
	s_setprio 1
	v_mfma_f32_16x16x32_bf16 v[122:125], v[166:169], v[182:185], v[122:125]
	v_mfma_f32_16x16x32_bf16 v[114:117], v[174:177], v[182:185], v[114:117]
	v_mfma_f32_16x16x32_bf16 v[106:109], v[166:169], v[190:193], v[106:109]
	v_mfma_f32_16x16x32_bf16 v[98:101], v[174:177], v[190:193], v[98:101]
	v_mfma_f32_16x16x32_bf16 v[90:93], v[166:169], v[198:201], v[90:93]
	v_mfma_f32_16x16x32_bf16 v[82:85], v[174:177], v[198:201], v[82:85]
	v_mfma_f32_16x16x32_bf16 v[74:77], v[166:169], v[214:217], v[74:77]
	v_mfma_f32_16x16x32_bf16 v[66:69], v[174:177], v[214:217], v[66:69]
	v_mfma_f32_16x16x32_bf16 v[122:125], v[170:173], v[186:189], v[122:125]
	v_mfma_f32_16x16x32_bf16 v[114:117], v[178:181], v[186:189], v[114:117]
	v_mfma_f32_16x16x32_bf16 v[106:109], v[170:173], v[194:197], v[106:109]
	v_mfma_f32_16x16x32_bf16 v[98:101], v[178:181], v[194:197], v[98:101]
	v_mfma_f32_16x16x32_bf16 v[90:93], v[170:173], v[210:213], v[90:93]
	v_mfma_f32_16x16x32_bf16 v[82:85], v[178:181], v[210:213], v[82:85]
	v_mfma_f32_16x16x32_bf16 v[74:77], v[170:173], v[218:221], v[74:77]
	v_mfma_f32_16x16x32_bf16 v[66:69], v[178:181], v[218:221], v[66:69]
	s_setprio 0
	s_barrier
	s_add_i32 s24, s51, s29
	v_lshl_add_u64 v[140:141], v[140:141], 0, s[4:5]
	s_mov_b32 m0, s24
	ds_read_b128 v[182:185], v145 offset:49152
	ds_read_b128 v[186:189], v145 offset:50176
	ds_read_b128 v[190:193], v145 offset:51200
	ds_read_b128 v[194:197], v145 offset:52224
	ds_read_b128 v[198:201], v145 offset:53248
	ds_read_b128 v[210:213], v145 offset:54272
	ds_read_b128 v[214:217], v145 offset:55296
	ds_read_b128 v[218:221], v145 offset:56320
	global_load_lds_dwordx4 v[140:141], off
	s_add_i32 m0, s24, 0x2000
	s_add_u32 s22, s22, 0x40080
	v_lshl_add_u64 v[140:141], v[202:203], 0, s[4:5]
	s_addc_u32 s23, s23, 0
	s_add_i32 s24, s52, s29
	global_load_lds_dwordx4 v[140:141], off
	v_lshl_add_u64 v[140:141], s[22:23], 0, v[0:1]
	s_mov_b32 m0, s24
	s_nop 0
	global_load_lds_dwordx4 v[140:141], off
	v_lshl_add_u64 v[140:141], s[22:23], 0, v[130:131]
	s_add_i32 m0, s24, 0x2000
	s_nop 0
	global_load_lds_dwordx4 v[140:141], off
	v_lshl_add_u64 v[140:141], v[206:207], 0, s[4:5]
	s_mov_b32 m0, s40
	s_nop 0
	global_load_lds_dwordx4 v[140:141], off
	v_lshl_add_u64 v[140:141], v[222:223], 0, s[4:5]
	s_mov_b32 m0, s41
	s_nop 0
	global_load_lds_dwordx4 v[140:141], off
	s_waitcnt vmcnt(8)
	s_waitcnt lgkmcnt(0)
	s_barrier
	s_setprio 1
	s_waitcnt lgkmcnt(0)
	v_mfma_f32_16x16x32_bf16 v[62:65], v[146:149], v[182:185], v[62:65]
	v_mfma_f32_16x16x32_bf16 v[54:57], v[154:157], v[182:185], v[54:57]
	v_mfma_f32_16x16x32_bf16 v[46:49], v[146:149], v[190:193], v[46:49]
	v_mfma_f32_16x16x32_bf16 v[38:41], v[154:157], v[190:193], v[38:41]
	v_mfma_f32_16x16x32_bf16 v[30:33], v[146:149], v[198:201], v[30:33]
	v_mfma_f32_16x16x32_bf16 v[22:25], v[154:157], v[198:201], v[22:25]
	v_mfma_f32_16x16x32_bf16 v[14:17], v[146:149], v[214:217], v[14:17]
	v_mfma_f32_16x16x32_bf16 v[6:9], v[154:157], v[214:217], v[6:9]
	v_mfma_f32_16x16x32_bf16 v[62:65], v[150:153], v[186:189], v[62:65]
	v_mfma_f32_16x16x32_bf16 v[54:57], v[158:161], v[186:189], v[54:57]
	v_mfma_f32_16x16x32_bf16 v[46:49], v[150:153], v[194:197], v[46:49]
	v_mfma_f32_16x16x32_bf16 v[38:41], v[158:161], v[194:197], v[38:41]
	v_mfma_f32_16x16x32_bf16 v[30:33], v[150:153], v[210:213], v[30:33]
	v_mfma_f32_16x16x32_bf16 v[22:25], v[158:161], v[210:213], v[22:25]
	v_mfma_f32_16x16x32_bf16 v[14:17], v[150:153], v[218:221], v[14:17]
	v_mfma_f32_16x16x32_bf16 v[6:9], v[158:161], v[218:221], v[6:9]
	s_setprio 0
	s_setprio 1
	v_mfma_f32_16x16x32_bf16 v[58:61], v[166:169], v[182:185], v[58:61]
	v_mfma_f32_16x16x32_bf16 v[50:53], v[174:177], v[182:185], v[50:53]
	v_mfma_f32_16x16x32_bf16 v[42:45], v[166:169], v[190:193], v[42:45]
	v_mfma_f32_16x16x32_bf16 v[34:37], v[174:177], v[190:193], v[34:37]
	v_mfma_f32_16x16x32_bf16 v[26:29], v[166:169], v[198:201], v[26:29]
	v_mfma_f32_16x16x32_bf16 v[18:21], v[174:177], v[198:201], v[18:21]
	v_mfma_f32_16x16x32_bf16 v[10:13], v[166:169], v[214:217], v[10:13]
	v_mfma_f32_16x16x32_bf16 v[2:5], v[174:177], v[214:217], v[2:5]
	v_mfma_f32_16x16x32_bf16 v[58:61], v[170:173], v[186:189], v[58:61]
	v_mfma_f32_16x16x32_bf16 v[50:53], v[178:181], v[186:189], v[50:53]
	v_mfma_f32_16x16x32_bf16 v[42:45], v[170:173], v[194:197], v[42:45]
	v_mfma_f32_16x16x32_bf16 v[34:37], v[178:181], v[194:197], v[34:37]
	v_mfma_f32_16x16x32_bf16 v[26:29], v[170:173], v[210:213], v[26:29]
	v_mfma_f32_16x16x32_bf16 v[18:21], v[178:181], v[210:213], v[18:21]
	v_mfma_f32_16x16x32_bf16 v[10:13], v[170:173], v[218:221], v[10:13]
	v_mfma_f32_16x16x32_bf16 v[2:5], v[178:181], v[218:221], v[2:5]
	s_setprio 0
	s_add_i32 s50, s50, 2
	s_add_u32 s20, s20, 0x100
	s_addc_u32 s21, s21, 0
	s_add_u32 s48, s48, 0x100
	s_addc_u32 s49, s49, 0
	s_cmp_gt_u32 s50, 13
	s_barrier
	s_cbranch_scc0 .LBB0_684
	s_and_b64 vcc, exec, s[10:11]
	s_cbranch_vccz .LBB0_687
	s_barrier
